# strategy 1: the redundant post-barrier lgkmcnt(0) at the head of each MFMA block (already drained before the barrier) removed from all six GEMM K-loops, on top of v9
# speedup vs baseline: 1.0074x; 1.0074x over previous
; #define PG8_STAGE(bufoff, gbase, voff) do { _Pragma("unroll") for (int _i = 0; _i < 2; ++_i) \
;         __builtin_amdgcn_global_load_lds((const unsigned*)((const char*)(gbase) + (voff)[_i]), (PG8_LAS unsigned*)(lds + (bufoff) + ldsw + _i * 8192), 16, 0, 0); } while (0)
; #define PG8_LDA(dst, b, h) do { _Pragma("unroll") for (int m = 0; m < 4; ++m) _Pragma("unroll") for (int k = 0; k < 2; ++k) dst[m][k] = *(const PG8_LAS bf16x8*)(lds + PG8_SA(b, h) + aoff + m * 2048 + k * 1024); } while (0)
; #define PG8_LDB(dst, b, h) do { _Pragma("unroll") for (int n = 0; n < 2; ++n) _Pragma("unroll") for (int k = 0; k < 2; ++k) dst[n][k] = *(const PG8_LAS bf16x8*)(lds + PG8_SB(b, h) + boff + n * 2048 + k * 1024); } while (0)
; #define PG8_MMA(ai, bj, At, Bt) do { __builtin_amdgcn_s_setprio(1); _Pragma("unroll") for (int m = 0; m < 4; ++m) _Pragma("unroll") for (int n = 0; n < 2; ++n) _Pragma("unroll") for (int k = 0; k < 2; ++k) \
;         acc[ai][bj][m][n] = __builtin_amdgcn_mfma_f32_16x16x32_bf16(Bt[n][k], At[m][k], acc[ai][bj][m][n], 0, 0, 0); __builtin_amdgcn_s_setprio(0); } while (0)
; #define PG8_WAIT_V(n) asm volatile("s_waitcnt vmcnt(" #n ")" ::: "memory")
; #define PG8_BAR __builtin_amdgcn_s_barrier()
; template <class Epi, class Sched, bool ALIGN_EPI = false, bool SP2 = false>
; __device__ __forceinline__ void gemm_phase(PG8_LAS unsigned char* lds, const Gemm g, const Sched& S, const Epi& E) {
;     ...
;         for (int t = 0; t < nt; t += 2) {
;             const bool last = (t == nt - 2);
;             const char* a1 = cA + (size_t)(t + 1) * kstep;
;             const char* a2 = last ? nA : cA + (size_t)(t + 2) * kstep; const char* b2 = last ? nB : cB + (size_t)(t + 2) * kstep;
;             const char* a3 = a2 + kstep; const char* b3 = b2 + kstep;
;             if (last && has_next) S.a_ready(nxt);
;             if constexpr (SP2) {
;             PG8_LDB(B0, 0, 0); PG8_LDB(B1, 0, 1); PG8_SCHED; PG8_LDA(At, 0, 0); PG8_STAGE(PG8_SA(1, 1), a1 + hstep, voffA);
;             PG8_WAIT_V(8); PG8_WAIT_L(0); PG8_BAR; PG8_MMA(0, 0, At, B0); PG8_MMA(0, 1, At, B1); PG8_BAR; PG8_SCHED;
;             PG8_LDA(At, 0, 1); PG8_STAGE(PG8_SB(0, 0), b2, voffB); PG8_STAGE(PG8_SB(0, 1), b2 + hstep, voffB); PG8_STAGE(PG8_SA(0, 0), a2, voffA);
;             PG8_WAIT_V(8); PG8_WAIT_L(0); PG8_BAR; PG8_MMA(1, 0, At, B0); PG8_MMA(1, 1, At, B1); PG8_BAR; PG8_SCHED;
.LBB0_147:
	s_add_u32 s12, s56, 0xfff80080
	s_addc_u32 s13, s57, -1
	s_add_i32 s85, 0, 0x10000
	s_cmp_eq_u32 s84, 28
	s_cselect_b32 s61, s18, s13
	s_cselect_b32 s60, s19, s12
	v_add_u32_e32 v142, s85, v145
	s_cselect_b32 s59, s43, s73
	s_cselect_b32 s58, s47, s72
	s_add_i32 s92, 0, 0x14000
	ds_read_b128 v[148:151], v142
	ds_read_b128 v[152:155], v142 offset:1024
	ds_read_b128 v[156:159], v142 offset:2048
	ds_read_b128 v[160:163], v142 offset:3072
	v_add_u32_e32 v142, s92, v145
	ds_read_b128 v[164:167], v142
	ds_read_b128 v[168:171], v142 offset:1024
	ds_read_b128 v[172:175], v142 offset:2048
	ds_read_b128 v[176:179], v142 offset:3072
	v_lshl_add_u64 v[142:143], s[56:57], 0, v[140:141]
	s_add_i32 m0, s55, 0xc000
	ds_read_b128 v[180:183], v147
	ds_read_b128 v[184:187], v147 offset:1024
	ds_read_b128 v[188:191], v147 offset:2048
	ds_read_b128 v[202:205], v147 offset:3072
	ds_read_b128 v[206:209], v147 offset:4096
	ds_read_b128 v[210:213], v147 offset:5120
	ds_read_b128 v[214:217], v147 offset:6144
	ds_read_b128 v[218:221], v147 offset:7168
	global_load_lds_dwordx4 v[142:143], off
	v_lshl_add_u64 v[142:143], s[56:57], 0, v[138:139]
	s_add_i32 m0, s55, 0xe000
	s_nop 0
	global_load_lds_dwordx4 v[142:143], off
	s_waitcnt vmcnt(8)
	s_waitcnt lgkmcnt(0)
	s_barrier
	s_setprio 1
	v_mfma_f32_16x16x32_bf16 v[126:129], v[148:151], v[180:183], v[126:129]
	v_mfma_f32_16x16x32_bf16 v[122:125], v[156:159], v[180:183], v[122:125]
	v_mfma_f32_16x16x32_bf16 v[118:121], v[148:151], v[188:191], v[118:121]
	v_mfma_f32_16x16x32_bf16 v[110:113], v[156:159], v[188:191], v[110:113]
	v_mfma_f32_16x16x32_bf16 v[102:105], v[148:151], v[206:209], v[102:105]
	v_mfma_f32_16x16x32_bf16 v[92:95], v[156:159], v[206:209], v[92:95]
	v_mfma_f32_16x16x32_bf16 v[84:87], v[148:151], v[214:217], v[84:87]
	v_mfma_f32_16x16x32_bf16 v[76:79], v[156:159], v[214:217], v[76:79]
	v_mfma_f32_16x16x32_bf16 v[126:129], v[152:155], v[184:187], v[126:129]
	v_mfma_f32_16x16x32_bf16 v[122:125], v[160:163], v[184:187], v[122:125]
	v_mfma_f32_16x16x32_bf16 v[118:121], v[152:155], v[202:205], v[118:121]
	v_mfma_f32_16x16x32_bf16 v[110:113], v[160:163], v[202:205], v[110:113]
	v_mfma_f32_16x16x32_bf16 v[102:105], v[152:155], v[210:213], v[102:105]
	v_mfma_f32_16x16x32_bf16 v[92:95], v[160:163], v[210:213], v[92:95]
	v_mfma_f32_16x16x32_bf16 v[84:87], v[152:155], v[218:221], v[84:87]
	v_mfma_f32_16x16x32_bf16 v[76:79], v[160:163], v[218:221], v[76:79]
	s_setprio 0
	s_setprio 1
	v_mfma_f32_16x16x32_bf16 v[114:117], v[164:167], v[180:183], v[114:117]
	v_mfma_f32_16x16x32_bf16 v[106:109], v[172:175], v[180:183], v[106:109]
	v_mfma_f32_16x16x32_bf16 v[98:101], v[164:167], v[188:191], v[98:101]
	v_mfma_f32_16x16x32_bf16 v[88:91], v[172:175], v[188:191], v[88:91]
	v_mfma_f32_16x16x32_bf16 v[80:83], v[164:167], v[206:209], v[80:83]
	v_mfma_f32_16x16x32_bf16 v[72:75], v[172:175], v[206:209], v[72:75]
	v_mfma_f32_16x16x32_bf16 v[68:71], v[164:167], v[214:217], v[68:71]
	v_mfma_f32_16x16x32_bf16 v[64:67], v[172:175], v[214:217], v[64:67]
	v_mfma_f32_16x16x32_bf16 v[114:117], v[168:171], v[184:187], v[114:117]
	v_mfma_f32_16x16x32_bf16 v[106:109], v[176:179], v[184:187], v[106:109]
	v_mfma_f32_16x16x32_bf16 v[98:101], v[168:171], v[202:205], v[98:101]
	v_mfma_f32_16x16x32_bf16 v[88:91], v[176:179], v[202:205], v[88:91]
	v_mfma_f32_16x16x32_bf16 v[80:83], v[168:171], v[210:213], v[80:83]
	v_mfma_f32_16x16x32_bf16 v[72:75], v[176:179], v[210:213], v[72:75]
	v_mfma_f32_16x16x32_bf16 v[68:71], v[168:171], v[218:221], v[68:71]
	v_mfma_f32_16x16x32_bf16 v[64:67], v[176:179], v[218:221], v[64:67]
	s_setprio 0
	s_barrier
	s_add_i32 s12, s85, s63
	v_lshl_add_u64 v[142:143], s[58:59], 0, v[132:133]
	s_mov_b32 m0, s12
	ds_read_b128 v[180:183], v147 offset:16384
	ds_read_b128 v[184:187], v147 offset:17408
	ds_read_b128 v[188:191], v147 offset:18432
	ds_read_b128 v[202:205], v147 offset:19456
	ds_read_b128 v[206:209], v147 offset:20480
	ds_read_b128 v[210:213], v147 offset:21504
	ds_read_b128 v[214:217], v147 offset:22528
	ds_read_b128 v[218:221], v147 offset:23552
	global_load_lds_dwordx4 v[142:143], off
	s_add_i32 m0, s12, 0x2000
	s_add_u32 s12, s58, 0x80000
	v_lshl_add_u64 v[192:193], s[58:59], 0, v[136:137]
	s_addc_u32 s13, s59, 0
	s_add_i32 s85, s92, s63
	global_load_lds_dwordx4 v[192:193], off
	v_lshl_add_u64 v[222:223], s[12:13], 0, v[132:133]
	s_mov_b32 m0, s85
	v_lshl_add_u64 v[224:225], s[60:61], 0, v[134:135]
	global_load_lds_dwordx4 v[222:223], off
	v_lshl_add_u64 v[222:223], s[12:13], 0, v[136:137]
	s_add_i32 m0, s85, 0x2000
	s_nop 0
	global_load_lds_dwordx4 v[222:223], off
	v_lshl_add_u64 v[222:223], s[60:61], 0, v[130:131]
	s_mov_b32 m0, s55
	s_nop 0
	global_load_lds_dwordx4 v[222:223], off
	s_mov_b32 m0, s64
	s_nop 0
	global_load_lds_dwordx4 v[224:225], off
	s_waitcnt vmcnt(8)
	s_waitcnt lgkmcnt(0)
	s_barrier
; #define PG8_STAGE(bufoff, gbase, voff) do { _Pragma("unroll") for (int _i = 0; _i < 2; ++_i) \
;         __builtin_amdgcn_global_load_lds((const unsigned*)((const char*)(gbase) + (voff)[_i]), (PG8_LAS unsigned*)(lds + (bufoff) + ldsw + _i * 8192), 16, 0, 0); } while (0)
; #define PG8_LDA(dst, b, h) do { _Pragma("unroll") for (int m = 0; m < 4; ++m) _Pragma("unroll") for (int k = 0; k < 2; ++k) dst[m][k] = *(const PG8_LAS bf16x8*)(lds + PG8_SA(b, h) + aoff + m * 2048 + k * 1024); } while (0)
; #define PG8_LDB(dst, b, h) do { _Pragma("unroll") for (int n = 0; n < 2; ++n) _Pragma("unroll") for (int k = 0; k < 2; ++k) dst[n][k] = *(const PG8_LAS bf16x8*)(lds + PG8_SB(b, h) + boff + n * 2048 + k * 1024); } while (0)
; #define PG8_MMA(ai, bj, At, Bt) do { __builtin_amdgcn_s_setprio(1); _Pragma("unroll") for (int m = 0; m < 4; ++m) _Pragma("unroll") for (int n = 0; n < 2; ++n) _Pragma("unroll") for (int k = 0; k < 2; ++k) \
;         acc[ai][bj][m][n] = __builtin_amdgcn_mfma_f32_16x16x32_bf16(Bt[n][k], At[m][k], acc[ai][bj][m][n], 0, 0, 0); __builtin_amdgcn_s_setprio(0); } while (0)
; #define PG8_WAIT_V(n) asm volatile("s_waitcnt vmcnt(" #n ")" ::: "memory")
; #define PG8_WAIT_L(n) asm volatile("s_waitcnt lgkmcnt(" #n ")" ::: "memory")
; #define PG8_BAR __builtin_amdgcn_s_barrier()
; #define PG8_SCHED __builtin_amdgcn_sched_barrier(0)
; template <class Epi, class Sched, bool ALIGN_EPI = false, bool SP2 = false>
; __device__ __forceinline__ void gemm_phase(PG8_LAS unsigned char* lds, const Gemm g, const Sched& S, const Epi& E) {
;     ...
;             PG8_WAIT_V(8); PG8_WAIT_L(0); PG8_BAR; PG8_MMA(1, 0, At, B0); PG8_MMA(1, 1, At, B1); PG8_BAR; PG8_SCHED;
;             PG8_LDB(B0, 1, 0); PG8_LDB(B1, 1, 1); PG8_SCHED; PG8_LDA(At, 1, 0); PG8_STAGE(PG8_SA(0, 1), a2 + hstep, voffA);
;             PG8_WAIT_V(8); PG8_WAIT_L(0); PG8_BAR; PG8_MMA(0, 0, At, B0); PG8_MMA(0, 1, At, B1); PG8_BAR; PG8_SCHED;
	s_setprio 1
	v_mfma_f32_16x16x32_bf16 v[60:63], v[148:151], v[180:183], v[60:63]
	v_mfma_f32_16x16x32_bf16 v[56:59], v[156:159], v[180:183], v[56:59]
	v_mfma_f32_16x16x32_bf16 v[52:55], v[148:151], v[188:191], v[52:55]
	v_mfma_f32_16x16x32_bf16 v[44:47], v[156:159], v[188:191], v[44:47]
	v_mfma_f32_16x16x32_bf16 v[36:39], v[148:151], v[206:209], v[36:39]
	v_mfma_f32_16x16x32_bf16 v[28:31], v[156:159], v[206:209], v[28:31]
	v_mfma_f32_16x16x32_bf16 v[20:23], v[148:151], v[214:217], v[20:23]
	v_mfma_f32_16x16x32_bf16 v[12:15], v[156:159], v[214:217], v[12:15]
	v_mfma_f32_16x16x32_bf16 v[60:63], v[152:155], v[184:187], v[60:63]
	v_mfma_f32_16x16x32_bf16 v[56:59], v[160:163], v[184:187], v[56:59]
	v_mfma_f32_16x16x32_bf16 v[52:55], v[152:155], v[202:205], v[52:55]
	v_mfma_f32_16x16x32_bf16 v[44:47], v[160:163], v[202:205], v[44:47]
	v_mfma_f32_16x16x32_bf16 v[36:39], v[152:155], v[210:213], v[36:39]
	v_mfma_f32_16x16x32_bf16 v[28:31], v[160:163], v[210:213], v[28:31]
	v_mfma_f32_16x16x32_bf16 v[20:23], v[152:155], v[218:221], v[20:23]
	v_mfma_f32_16x16x32_bf16 v[12:15], v[160:163], v[218:221], v[12:15]
	s_setprio 0
	s_setprio 1
	v_mfma_f32_16x16x32_bf16 v[48:51], v[164:167], v[180:183], v[48:51]
	v_mfma_f32_16x16x32_bf16 v[40:43], v[172:175], v[180:183], v[40:43]
	v_mfma_f32_16x16x32_bf16 v[32:35], v[164:167], v[188:191], v[32:35]
	v_mfma_f32_16x16x32_bf16 v[24:27], v[172:175], v[188:191], v[24:27]
	v_mfma_f32_16x16x32_bf16 v[16:19], v[164:167], v[206:209], v[16:19]
	v_mfma_f32_16x16x32_bf16 v[8:11], v[172:175], v[206:209], v[8:11]
	v_mfma_f32_16x16x32_bf16 v[4:7], v[164:167], v[214:217], v[4:7]
	v_mfma_f32_16x16x32_bf16 v[0:3], v[172:175], v[214:217], v[0:3]
	v_mfma_f32_16x16x32_bf16 v[48:51], v[168:171], v[184:187], v[48:51]
	v_mfma_f32_16x16x32_bf16 v[40:43], v[176:179], v[184:187], v[40:43]
	v_mfma_f32_16x16x32_bf16 v[32:35], v[168:171], v[202:205], v[32:35]
	v_mfma_f32_16x16x32_bf16 v[24:27], v[176:179], v[202:205], v[24:27]
	v_mfma_f32_16x16x32_bf16 v[16:19], v[168:171], v[210:213], v[16:19]
	v_mfma_f32_16x16x32_bf16 v[8:11], v[176:179], v[210:213], v[8:11]
	v_mfma_f32_16x16x32_bf16 v[4:7], v[168:171], v[218:221], v[4:7]
	v_mfma_f32_16x16x32_bf16 v[0:3], v[176:179], v[218:221], v[0:3]
	s_setprio 0
	s_barrier
	s_add_i32 s85, 0, 0x18000
	s_add_i32 s92, 0, 0x1c000
	v_add_u32_e32 v160, s85, v145
	v_add_u32_e32 v176, s92, v145
	ds_read_b128 v[148:151], v160
	ds_read_b128 v[152:155], v160 offset:1024
	ds_read_b128 v[156:159], v160 offset:2048
	ds_read_b128 v[160:163], v160 offset:3072
	ds_read_b128 v[164:167], v176
	ds_read_b128 v[168:171], v176 offset:1024
	ds_read_b128 v[172:175], v176 offset:2048
	ds_read_b128 v[176:179], v176 offset:3072
	s_add_u32 s12, s60, 0x80000
	s_addc_u32 s13, s61, 0
	s_mov_b32 m0, s65
	v_lshl_add_u64 v[226:227], s[12:13], 0, v[130:131]
	ds_read_b128 v[180:183], v147 offset:32768
	ds_read_b128 v[184:187], v147 offset:33792
	ds_read_b128 v[188:191], v147 offset:34816
	ds_read_b128 v[202:205], v147 offset:35840
	ds_read_b128 v[206:209], v147 offset:36864
	ds_read_b128 v[210:213], v147 offset:37888
	ds_read_b128 v[214:217], v147 offset:38912
	ds_read_b128 v[218:221], v147 offset:39936
	global_load_lds_dwordx4 v[226:227], off
	v_lshl_add_u64 v[226:227], s[12:13], 0, v[134:135]
	s_mov_b32 m0, s67
	s_nop 0
	global_load_lds_dwordx4 v[226:227], off
	s_waitcnt vmcnt(8)
	s_waitcnt lgkmcnt(0)
	s_barrier
	s_setprio 1
	v_mfma_f32_16x16x32_bf16 v[126:129], v[148:151], v[180:183], v[126:129]
	v_mfma_f32_16x16x32_bf16 v[122:125], v[156:159], v[180:183], v[122:125]
	v_mfma_f32_16x16x32_bf16 v[118:121], v[148:151], v[188:191], v[118:121]
	v_mfma_f32_16x16x32_bf16 v[110:113], v[156:159], v[188:191], v[110:113]
	v_mfma_f32_16x16x32_bf16 v[102:105], v[148:151], v[206:209], v[102:105]
	v_mfma_f32_16x16x32_bf16 v[92:95], v[156:159], v[206:209], v[92:95]
	v_mfma_f32_16x16x32_bf16 v[84:87], v[148:151], v[214:217], v[84:87]
	v_mfma_f32_16x16x32_bf16 v[76:79], v[156:159], v[214:217], v[76:79]
	v_mfma_f32_16x16x32_bf16 v[126:129], v[152:155], v[184:187], v[126:129]
	v_mfma_f32_16x16x32_bf16 v[122:125], v[160:163], v[184:187], v[122:125]
	v_mfma_f32_16x16x32_bf16 v[118:121], v[152:155], v[202:205], v[118:121]
	v_mfma_f32_16x16x32_bf16 v[110:113], v[160:163], v[202:205], v[110:113]
	v_mfma_f32_16x16x32_bf16 v[102:105], v[152:155], v[210:213], v[102:105]
	v_mfma_f32_16x16x32_bf16 v[92:95], v[160:163], v[210:213], v[92:95]
	v_mfma_f32_16x16x32_bf16 v[84:87], v[152:155], v[218:221], v[84:87]
	v_mfma_f32_16x16x32_bf16 v[76:79], v[160:163], v[218:221], v[76:79]
	s_setprio 0
	s_setprio 1
	v_mfma_f32_16x16x32_bf16 v[114:117], v[164:167], v[180:183], v[114:117]
	v_mfma_f32_16x16x32_bf16 v[106:109], v[172:175], v[180:183], v[106:109]
	v_mfma_f32_16x16x32_bf16 v[98:101], v[164:167], v[188:191], v[98:101]
	v_mfma_f32_16x16x32_bf16 v[88:91], v[172:175], v[188:191], v[88:91]
	v_mfma_f32_16x16x32_bf16 v[80:83], v[164:167], v[206:209], v[80:83]
	v_mfma_f32_16x16x32_bf16 v[72:75], v[172:175], v[206:209], v[72:75]
	v_mfma_f32_16x16x32_bf16 v[68:71], v[164:167], v[214:217], v[68:71]
	v_mfma_f32_16x16x32_bf16 v[64:67], v[172:175], v[214:217], v[64:67]
	v_mfma_f32_16x16x32_bf16 v[114:117], v[168:171], v[184:187], v[114:117]
	v_mfma_f32_16x16x32_bf16 v[106:109], v[176:179], v[184:187], v[106:109]
	v_mfma_f32_16x16x32_bf16 v[98:101], v[168:171], v[202:205], v[98:101]
	v_mfma_f32_16x16x32_bf16 v[88:91], v[176:179], v[202:205], v[88:91]
	v_mfma_f32_16x16x32_bf16 v[80:83], v[168:171], v[210:213], v[80:83]
	v_mfma_f32_16x16x32_bf16 v[72:75], v[176:179], v[210:213], v[72:75]
	v_mfma_f32_16x16x32_bf16 v[68:71], v[168:171], v[218:221], v[68:71]
	v_mfma_f32_16x16x32_bf16 v[64:67], v[176:179], v[218:221], v[64:67]
	s_setprio 0
	s_barrier
; #define PG8_STAGE(bufoff, gbase, voff) do { _Pragma("unroll") for (int _i = 0; _i < 2; ++_i) \
;         __builtin_amdgcn_global_load_lds((const unsigned*)((const char*)(gbase) + (voff)[_i]), (PG8_LAS unsigned*)(lds + (bufoff) + ldsw + _i * 8192), 16, 0, 0); } while (0)
; #define PG8_LDA(dst, b, h) do { _Pragma("unroll") for (int m = 0; m < 4; ++m) _Pragma("unroll") for (int k = 0; k < 2; ++k) dst[m][k] = *(const PG8_LAS bf16x8*)(lds + PG8_SA(b, h) + aoff + m * 2048 + k * 1024); } while (0)
; #define PG8_MMA(ai, bj, At, Bt) do { __builtin_amdgcn_s_setprio(1); _Pragma("unroll") for (int m = 0; m < 4; ++m) _Pragma("unroll") for (int n = 0; n < 2; ++n) _Pragma("unroll") for (int k = 0; k < 2; ++k) \
;         acc[ai][bj][m][n] = __builtin_amdgcn_mfma_f32_16x16x32_bf16(Bt[n][k], At[m][k], acc[ai][bj][m][n], 0, 0, 0); __builtin_amdgcn_s_setprio(0); } while (0)
; #define PG8_WAIT_V(n) asm volatile("s_waitcnt vmcnt(" #n ")" ::: "memory")
; #define PG8_WAIT_L(n) asm volatile("s_waitcnt lgkmcnt(" #n ")" ::: "memory")
; #define PG8_BAR __builtin_amdgcn_s_barrier()
; #define PG8_SCHED __builtin_amdgcn_sched_barrier(0)
; template <class Epi, class Sched, bool ALIGN_EPI = false, bool SP2 = false>
; __device__ __forceinline__ void gemm_phase(PG8_LAS unsigned char* lds, const Gemm g, const Sched& S, const Epi& E) {
;     ...
;         for (int t = 0; t < nt; t += 2) {
;             const bool last = (t == nt - 2);
;     ...
;             PG8_LDA(At, 1, 1); PG8_STAGE(PG8_SB(1, 0), b3, voffB); PG8_STAGE(PG8_SB(1, 1), b3 + hstep, voffB); PG8_STAGE(PG8_SA(1, 0), a3, voffA);
;             PG8_WAIT_V(8); PG8_WAIT_L(0); PG8_BAR; PG8_MMA(1, 0, At, B0); PG8_MMA(1, 1, At, B1); PG8_BAR; PG8_SCHED;
	s_add_i32 s12, s85, s63
	v_lshl_add_u64 v[142:143], v[142:143], 0, s[36:37]
	s_mov_b32 m0, s12
	ds_read_b128 v[180:183], v147 offset:49152
	ds_read_b128 v[184:187], v147 offset:50176
	ds_read_b128 v[188:191], v147 offset:51200
	ds_read_b128 v[202:205], v147 offset:52224
	ds_read_b128 v[206:209], v147 offset:53248
	ds_read_b128 v[210:213], v147 offset:54272
	ds_read_b128 v[214:217], v147 offset:55296
	ds_read_b128 v[218:221], v147 offset:56320
	global_load_lds_dwordx4 v[142:143], off
	s_add_i32 m0, s12, 0x2000
	s_add_u32 s12, s58, 0x80080
	v_lshl_add_u64 v[142:143], v[192:193], 0, s[36:37]
	s_addc_u32 s13, s59, 0
	s_add_i32 s58, s92, s63
	global_load_lds_dwordx4 v[142:143], off
	v_lshl_add_u64 v[142:143], s[12:13], 0, v[132:133]
	s_mov_b32 m0, s58
	s_nop 0
	global_load_lds_dwordx4 v[142:143], off
	v_lshl_add_u64 v[142:143], s[12:13], 0, v[136:137]
	s_add_i32 m0, s58, 0x2000
	s_nop 0
	global_load_lds_dwordx4 v[142:143], off
	v_lshl_add_u64 v[142:143], v[222:223], 0, s[36:37]
	s_mov_b32 m0, s68
	s_nop 0
	global_load_lds_dwordx4 v[142:143], off
	v_lshl_add_u64 v[142:143], v[224:225], 0, s[36:37]
	s_mov_b32 m0, s69
	s_nop 0
	global_load_lds_dwordx4 v[142:143], off
	s_waitcnt vmcnt(8)
	s_waitcnt lgkmcnt(0)
	s_barrier
	s_setprio 1
	v_mfma_f32_16x16x32_bf16 v[60:63], v[148:151], v[180:183], v[60:63]
	v_mfma_f32_16x16x32_bf16 v[56:59], v[156:159], v[180:183], v[56:59]
	v_mfma_f32_16x16x32_bf16 v[52:55], v[148:151], v[188:191], v[52:55]
	v_mfma_f32_16x16x32_bf16 v[44:47], v[156:159], v[188:191], v[44:47]
	v_mfma_f32_16x16x32_bf16 v[36:39], v[148:151], v[206:209], v[36:39]
	v_mfma_f32_16x16x32_bf16 v[28:31], v[156:159], v[206:209], v[28:31]
	v_mfma_f32_16x16x32_bf16 v[20:23], v[148:151], v[214:217], v[20:23]
	v_mfma_f32_16x16x32_bf16 v[12:15], v[156:159], v[214:217], v[12:15]
	v_mfma_f32_16x16x32_bf16 v[60:63], v[152:155], v[184:187], v[60:63]
	v_mfma_f32_16x16x32_bf16 v[56:59], v[160:163], v[184:187], v[56:59]
	v_mfma_f32_16x16x32_bf16 v[52:55], v[152:155], v[202:205], v[52:55]
	v_mfma_f32_16x16x32_bf16 v[44:47], v[160:163], v[202:205], v[44:47]
	v_mfma_f32_16x16x32_bf16 v[36:39], v[152:155], v[210:213], v[36:39]
	v_mfma_f32_16x16x32_bf16 v[28:31], v[160:163], v[210:213], v[28:31]
	v_mfma_f32_16x16x32_bf16 v[20:23], v[152:155], v[218:221], v[20:23]
	v_mfma_f32_16x16x32_bf16 v[12:15], v[160:163], v[218:221], v[12:15]
	s_setprio 0
	s_setprio 1
	v_mfma_f32_16x16x32_bf16 v[48:51], v[164:167], v[180:183], v[48:51]
	v_mfma_f32_16x16x32_bf16 v[40:43], v[172:175], v[180:183], v[40:43]
	v_mfma_f32_16x16x32_bf16 v[32:35], v[164:167], v[188:191], v[32:35]
	v_mfma_f32_16x16x32_bf16 v[24:27], v[172:175], v[188:191], v[24:27]
	v_mfma_f32_16x16x32_bf16 v[16:19], v[164:167], v[206:209], v[16:19]
	v_mfma_f32_16x16x32_bf16 v[8:11], v[172:175], v[206:209], v[8:11]
	v_mfma_f32_16x16x32_bf16 v[4:7], v[164:167], v[214:217], v[4:7]
	v_mfma_f32_16x16x32_bf16 v[0:3], v[172:175], v[214:217], v[0:3]
	v_mfma_f32_16x16x32_bf16 v[48:51], v[168:171], v[184:187], v[48:51]
	v_mfma_f32_16x16x32_bf16 v[40:43], v[176:179], v[184:187], v[40:43]
	v_mfma_f32_16x16x32_bf16 v[32:35], v[168:171], v[202:205], v[32:35]
	v_mfma_f32_16x16x32_bf16 v[24:27], v[176:179], v[202:205], v[24:27]
	v_mfma_f32_16x16x32_bf16 v[16:19], v[168:171], v[210:213], v[16:19]
	v_mfma_f32_16x16x32_bf16 v[8:11], v[176:179], v[210:213], v[8:11]
	v_mfma_f32_16x16x32_bf16 v[4:7], v[168:171], v[218:221], v[4:7]
	v_mfma_f32_16x16x32_bf16 v[0:3], v[176:179], v[218:221], v[0:3]
	s_setprio 0
	s_barrier
	s_add_i32 s84, s84, 2
	s_add_u32 s72, s72, 0x100
	s_addc_u32 s73, s73, 0
	s_add_u32 s56, s56, 0x100
	s_addc_u32 s57, s57, 0
	s_cmp_gt_u32 s84, 29
	s_cbranch_scc0 .LBB0_147
	s_and_b64 vcc, exec, s[14:15]
	s_cbranch_vccz .LBB0_150
	s_barrier

; #define PG8_STAGE(bufoff, gbase, voff) do { _Pragma("unroll") for (int _i = 0; _i < 2; ++_i) \
;         __builtin_amdgcn_global_load_lds((const unsigned*)((const char*)(gbase) + (voff)[_i]), (PG8_LAS unsigned*)(lds + (bufoff) + ldsw + _i * 8192), 16, 0, 0); } while (0)
; #define PG8_LDA(dst, b, h) do { _Pragma("unroll") for (int m = 0; m < 4; ++m) _Pragma("unroll") for (int k = 0; k < 2; ++k) dst[m][k] = *(const PG8_LAS bf16x8*)(lds + PG8_SA(b, h) + aoff + m * 2048 + k * 1024); } while (0)
; #define PG8_LDB(dst, b, h) do { _Pragma("unroll") for (int n = 0; n < 2; ++n) _Pragma("unroll") for (int k = 0; k < 2; ++k) dst[n][k] = *(const PG8_LAS bf16x8*)(lds + PG8_SB(b, h) + boff + n * 2048 + k * 1024); } while (0)
; #define PG8_MMA(ai, bj, At, Bt) do { __builtin_amdgcn_s_setprio(1); _Pragma("unroll") for (int m = 0; m < 4; ++m) _Pragma("unroll") for (int n = 0; n < 2; ++n) _Pragma("unroll") for (int k = 0; k < 2; ++k) \
;         acc[ai][bj][m][n] = __builtin_amdgcn_mfma_f32_16x16x32_bf16(Bt[n][k], At[m][k], acc[ai][bj][m][n], 0, 0, 0); __builtin_amdgcn_s_setprio(0); } while (0)
; #define PG8_WAIT_V(n) asm volatile("s_waitcnt vmcnt(" #n ")" ::: "memory")
; #define PG8_BAR __builtin_amdgcn_s_barrier()
; template <class Epi, class Sched, bool ALIGN_EPI = false, bool SP2 = false>
; __device__ __forceinline__ void gemm_phase(PG8_LAS unsigned char* lds, const Gemm g, const Sched& S, const Epi& E) {
;     ...
;         for (int t = 0; t < nt; t += 2) {
;             const bool last = (t == nt - 2);
;             const char* a1 = cA + (size_t)(t + 1) * kstep;
;             const char* a2 = last ? nA : cA + (size_t)(t + 2) * kstep; const char* b2 = last ? nB : cB + (size_t)(t + 2) * kstep;
;             const char* a3 = a2 + kstep; const char* b3 = b2 + kstep;
;             if (last && has_next) S.a_ready(nxt);
;             if constexpr (SP2) {
;             PG8_LDB(B0, 0, 0); PG8_LDB(B1, 0, 1); PG8_SCHED; PG8_LDA(At, 0, 0); PG8_STAGE(PG8_SA(1, 1), a1 + hstep, voffA);
;             PG8_WAIT_V(8); PG8_WAIT_L(0); PG8_BAR; PG8_MMA(0, 0, At, B0); PG8_MMA(0, 1, At, B1); PG8_BAR; PG8_SCHED;
;             PG8_LDA(At, 0, 1); PG8_STAGE(PG8_SB(0, 0), b2, voffB); PG8_STAGE(PG8_SB(0, 1), b2 + hstep, voffB); PG8_STAGE(PG8_SA(0, 0), a2, voffA);
;             PG8_WAIT_V(8); PG8_WAIT_L(0); PG8_BAR; PG8_MMA(1, 0, At, B0); PG8_MMA(1, 1, At, B1); PG8_BAR; PG8_SCHED;
.LBB0_175:
	s_add_u32 s12, s42, 0xfff80080
	s_addc_u32 s13, s43, -1
	s_add_i32 vcc_lo, 0, 0x10000
	s_cmp_eq_u32 s55, 28
	s_cselect_b32 s65, s10, s13
	s_cselect_b32 s64, s11, s12
	v_add_u32_e32 v148, vcc_lo, v150
	s_cselect_b32 s63, s5, s19
	s_cselect_b32 s62, s15, s18
	s_add_i32 vcc_hi, 0, 0x14000
	ds_read_b128 v[144:147], v148
	ds_read_b128 v[154:157], v148 offset:1024
	ds_read_b128 v[158:161], v148 offset:2048
	ds_read_b128 v[162:165], v148 offset:3072
	v_add_u32_e32 v148, vcc_hi, v150
	ds_read_b128 v[166:169], v148
	ds_read_b128 v[170:173], v148 offset:1024
	ds_read_b128 v[174:177], v148 offset:2048
	ds_read_b128 v[178:181], v148 offset:3072
	v_lshl_add_u64 v[222:223], s[42:43], 0, v[142:143]
	s_add_i32 m0, s61, 0xc000
	ds_read_b128 v[182:185], v153
	ds_read_b128 v[186:189], v153 offset:1024
	ds_read_b128 v[190:193], v153 offset:2048
	ds_read_b128 v[202:205], v153 offset:3072
	ds_read_b128 v[206:209], v153 offset:4096
	ds_read_b128 v[210:213], v153 offset:5120
	ds_read_b128 v[214:217], v153 offset:6144
	ds_read_b128 v[218:221], v153 offset:7168
	global_load_lds_dwordx4 v[222:223], off
	v_lshl_add_u64 v[222:223], s[42:43], 0, v[140:141]
	s_add_i32 m0, s61, 0xe000
	s_nop 0
	global_load_lds_dwordx4 v[222:223], off
	s_waitcnt vmcnt(8)
	s_waitcnt lgkmcnt(0)
	s_barrier
	s_setprio 1
	v_mfma_f32_16x16x32_bf16 v[126:129], v[144:147], v[182:185], v[126:129]
	v_mfma_f32_16x16x32_bf16 v[122:125], v[158:161], v[182:185], v[122:125]
	v_mfma_f32_16x16x32_bf16 v[110:113], v[144:147], v[190:193], v[110:113]
	v_mfma_f32_16x16x32_bf16 v[106:109], v[158:161], v[190:193], v[106:109]
	v_mfma_f32_16x16x32_bf16 v[92:95], v[144:147], v[206:209], v[92:95]
	v_mfma_f32_16x16x32_bf16 v[88:91], v[158:161], v[206:209], v[88:91]
	v_mfma_f32_16x16x32_bf16 v[76:79], v[144:147], v[214:217], v[76:79]
	v_mfma_f32_16x16x32_bf16 v[72:75], v[158:161], v[214:217], v[72:75]
	v_mfma_f32_16x16x32_bf16 v[126:129], v[154:157], v[186:189], v[126:129]
	v_mfma_f32_16x16x32_bf16 v[122:125], v[162:165], v[186:189], v[122:125]
	v_mfma_f32_16x16x32_bf16 v[110:113], v[154:157], v[202:205], v[110:113]
	v_mfma_f32_16x16x32_bf16 v[106:109], v[162:165], v[202:205], v[106:109]
	v_mfma_f32_16x16x32_bf16 v[92:95], v[154:157], v[210:213], v[92:95]
	v_mfma_f32_16x16x32_bf16 v[88:91], v[162:165], v[210:213], v[88:91]
	v_mfma_f32_16x16x32_bf16 v[76:79], v[154:157], v[218:221], v[76:79]
	v_mfma_f32_16x16x32_bf16 v[72:75], v[162:165], v[218:221], v[72:75]
	s_setprio 0
	s_setprio 1
	v_mfma_f32_16x16x32_bf16 v[118:121], v[166:169], v[182:185], v[118:121]
	v_mfma_f32_16x16x32_bf16 v[114:117], v[174:177], v[182:185], v[114:117]
	v_mfma_f32_16x16x32_bf16 v[102:105], v[166:169], v[190:193], v[102:105]
	v_mfma_f32_16x16x32_bf16 v[98:101], v[174:177], v[190:193], v[98:101]
	v_mfma_f32_16x16x32_bf16 v[84:87], v[166:169], v[206:209], v[84:87]
	v_mfma_f32_16x16x32_bf16 v[80:83], v[174:177], v[206:209], v[80:83]
	v_mfma_f32_16x16x32_bf16 v[68:71], v[166:169], v[214:217], v[68:71]
	v_mfma_f32_16x16x32_bf16 v[64:67], v[174:177], v[214:217], v[64:67]
	v_mfma_f32_16x16x32_bf16 v[118:121], v[170:173], v[186:189], v[118:121]
	v_mfma_f32_16x16x32_bf16 v[114:117], v[178:181], v[186:189], v[114:117]
	v_mfma_f32_16x16x32_bf16 v[102:105], v[170:173], v[202:205], v[102:105]
	v_mfma_f32_16x16x32_bf16 v[98:101], v[178:181], v[202:205], v[98:101]
	v_mfma_f32_16x16x32_bf16 v[84:87], v[170:173], v[210:213], v[84:87]
	v_mfma_f32_16x16x32_bf16 v[80:83], v[178:181], v[210:213], v[80:83]
	v_mfma_f32_16x16x32_bf16 v[68:71], v[170:173], v[218:221], v[68:71]
	v_mfma_f32_16x16x32_bf16 v[64:67], v[178:181], v[218:221], v[64:67]
	s_setprio 0
	s_barrier
	s_add_i32 s12, vcc_lo, s70
	v_lshl_add_u64 v[222:223], s[62:63], 0, v[132:133]
	s_mov_b32 m0, s12
	ds_read_b128 v[182:185], v153 offset:16384
	ds_read_b128 v[186:189], v153 offset:17408
	ds_read_b128 v[190:193], v153 offset:18432
	ds_read_b128 v[202:205], v153 offset:19456
	ds_read_b128 v[206:209], v153 offset:20480
	ds_read_b128 v[210:213], v153 offset:21504
	ds_read_b128 v[214:217], v153 offset:22528
	ds_read_b128 v[218:221], v153 offset:23552
	global_load_lds_dwordx4 v[222:223], off
	s_add_i32 m0, s12, 0x2000
	s_add_u32 s12, s62, 0x80000
	v_lshl_add_u64 v[224:225], s[62:63], 0, v[136:137]
	s_addc_u32 s13, s63, 0
	s_add_i32 vcc_lo, vcc_hi, s70
	global_load_lds_dwordx4 v[224:225], off
	v_lshl_add_u64 v[226:227], s[12:13], 0, v[132:133]
	s_mov_b32 m0, vcc_lo
	v_lshl_add_u64 v[228:229], s[64:65], 0, v[134:135]
	global_load_lds_dwordx4 v[226:227], off
	v_lshl_add_u64 v[226:227], s[12:13], 0, v[136:137]
	s_add_i32 m0, vcc_lo, 0x2000
	s_nop 0
	global_load_lds_dwordx4 v[226:227], off
	v_lshl_add_u64 v[226:227], s[64:65], 0, v[130:131]
	s_mov_b32 m0, s61
	s_nop 0
	global_load_lds_dwordx4 v[226:227], off
	s_mov_b32 m0, s72
	s_nop 0
	global_load_lds_dwordx4 v[228:229], off
	s_waitcnt vmcnt(8)
	s_waitcnt lgkmcnt(0)
	s_barrier
; #define PG8_STAGE(bufoff, gbase, voff) do { _Pragma("unroll") for (int _i = 0; _i < 2; ++_i) \
;         __builtin_amdgcn_global_load_lds((const unsigned*)((const char*)(gbase) + (voff)[_i]), (PG8_LAS unsigned*)(lds + (bufoff) + ldsw + _i * 8192), 16, 0, 0); } while (0)
; #define PG8_LDA(dst, b, h) do { _Pragma("unroll") for (int m = 0; m < 4; ++m) _Pragma("unroll") for (int k = 0; k < 2; ++k) dst[m][k] = *(const PG8_LAS bf16x8*)(lds + PG8_SA(b, h) + aoff + m * 2048 + k * 1024); } while (0)
; #define PG8_LDB(dst, b, h) do { _Pragma("unroll") for (int n = 0; n < 2; ++n) _Pragma("unroll") for (int k = 0; k < 2; ++k) dst[n][k] = *(const PG8_LAS bf16x8*)(lds + PG8_SB(b, h) + boff + n * 2048 + k * 1024); } while (0)
; #define PG8_MMA(ai, bj, At, Bt) do { __builtin_amdgcn_s_setprio(1); _Pragma("unroll") for (int m = 0; m < 4; ++m) _Pragma("unroll") for (int n = 0; n < 2; ++n) _Pragma("unroll") for (int k = 0; k < 2; ++k) \
;         acc[ai][bj][m][n] = __builtin_amdgcn_mfma_f32_16x16x32_bf16(Bt[n][k], At[m][k], acc[ai][bj][m][n], 0, 0, 0); __builtin_amdgcn_s_setprio(0); } while (0)
; #define PG8_WAIT_V(n) asm volatile("s_waitcnt vmcnt(" #n ")" ::: "memory")
; #define PG8_WAIT_L(n) asm volatile("s_waitcnt lgkmcnt(" #n ")" ::: "memory")
; #define PG8_BAR __builtin_amdgcn_s_barrier()
; #define PG8_SCHED __builtin_amdgcn_sched_barrier(0)
; template <class Epi, class Sched, bool ALIGN_EPI = false, bool SP2 = false>
; __device__ __forceinline__ void gemm_phase(PG8_LAS unsigned char* lds, const Gemm g, const Sched& S, const Epi& E) {
;     ...
;             PG8_WAIT_V(8); PG8_WAIT_L(0); PG8_BAR; PG8_MMA(1, 0, At, B0); PG8_MMA(1, 1, At, B1); PG8_BAR; PG8_SCHED;
;             PG8_LDB(B0, 1, 0); PG8_LDB(B1, 1, 1); PG8_SCHED; PG8_LDA(At, 1, 0); PG8_STAGE(PG8_SA(0, 1), a2 + hstep, voffA);
;             PG8_WAIT_V(8); PG8_WAIT_L(0); PG8_BAR; PG8_MMA(0, 0, At, B0); PG8_MMA(0, 1, At, B1); PG8_BAR; PG8_SCHED;
	s_setprio 1
	v_mfma_f32_16x16x32_bf16 v[60:63], v[144:147], v[182:185], v[60:63]
	v_mfma_f32_16x16x32_bf16 v[56:59], v[158:161], v[182:185], v[56:59]
	v_mfma_f32_16x16x32_bf16 v[44:47], v[144:147], v[190:193], v[44:47]
	v_mfma_f32_16x16x32_bf16 v[40:43], v[158:161], v[190:193], v[40:43]
	v_mfma_f32_16x16x32_bf16 v[28:31], v[144:147], v[206:209], v[28:31]
	v_mfma_f32_16x16x32_bf16 v[24:27], v[158:161], v[206:209], v[24:27]
	v_mfma_f32_16x16x32_bf16 v[12:15], v[144:147], v[214:217], v[12:15]
	v_mfma_f32_16x16x32_bf16 v[8:11], v[158:161], v[214:217], v[8:11]
	v_mfma_f32_16x16x32_bf16 v[60:63], v[154:157], v[186:189], v[60:63]
	v_mfma_f32_16x16x32_bf16 v[56:59], v[162:165], v[186:189], v[56:59]
	v_mfma_f32_16x16x32_bf16 v[44:47], v[154:157], v[202:205], v[44:47]
	v_mfma_f32_16x16x32_bf16 v[40:43], v[162:165], v[202:205], v[40:43]
	v_mfma_f32_16x16x32_bf16 v[28:31], v[154:157], v[210:213], v[28:31]
	v_mfma_f32_16x16x32_bf16 v[24:27], v[162:165], v[210:213], v[24:27]
	v_mfma_f32_16x16x32_bf16 v[12:15], v[154:157], v[218:221], v[12:15]
	v_mfma_f32_16x16x32_bf16 v[8:11], v[162:165], v[218:221], v[8:11]
	s_setprio 0
	s_setprio 1
	v_mfma_f32_16x16x32_bf16 v[52:55], v[166:169], v[182:185], v[52:55]
	v_mfma_f32_16x16x32_bf16 v[48:51], v[174:177], v[182:185], v[48:51]
	v_mfma_f32_16x16x32_bf16 v[36:39], v[166:169], v[190:193], v[36:39]
	v_mfma_f32_16x16x32_bf16 v[32:35], v[174:177], v[190:193], v[32:35]
	v_mfma_f32_16x16x32_bf16 v[20:23], v[166:169], v[206:209], v[20:23]
	v_mfma_f32_16x16x32_bf16 v[16:19], v[174:177], v[206:209], v[16:19]
	v_mfma_f32_16x16x32_bf16 v[4:7], v[166:169], v[214:217], v[4:7]
	v_mfma_f32_16x16x32_bf16 v[0:3], v[174:177], v[214:217], v[0:3]
	v_mfma_f32_16x16x32_bf16 v[52:55], v[170:173], v[186:189], v[52:55]
	v_mfma_f32_16x16x32_bf16 v[48:51], v[178:181], v[186:189], v[48:51]
	v_mfma_f32_16x16x32_bf16 v[36:39], v[170:173], v[202:205], v[36:39]
	v_mfma_f32_16x16x32_bf16 v[32:35], v[178:181], v[202:205], v[32:35]
	v_mfma_f32_16x16x32_bf16 v[20:23], v[170:173], v[210:213], v[20:23]
	v_mfma_f32_16x16x32_bf16 v[16:19], v[178:181], v[210:213], v[16:19]
	v_mfma_f32_16x16x32_bf16 v[4:7], v[170:173], v[218:221], v[4:7]
	v_mfma_f32_16x16x32_bf16 v[0:3], v[178:181], v[218:221], v[0:3]
	s_setprio 0
	s_barrier
	s_add_i32 vcc_lo, 0, 0x18000
	v_add_u32_e32 v148, vcc_lo, v150
	s_add_i32 vcc_hi, 0, 0x1c000
	ds_read_b128 v[144:147], v148
	ds_read_b128 v[154:157], v148 offset:1024
	ds_read_b128 v[158:161], v148 offset:2048
	ds_read_b128 v[162:165], v148 offset:3072
	v_add_u32_e32 v148, vcc_hi, v150
	ds_read_b128 v[166:169], v148
	ds_read_b128 v[170:173], v148 offset:1024
	ds_read_b128 v[174:177], v148 offset:2048
	ds_read_b128 v[178:181], v148 offset:3072
	s_add_u32 s12, s64, 0x80000
	s_addc_u32 s13, s65, 0
	s_mov_b32 m0, s73
	v_lshl_add_u64 v[230:231], s[12:13], 0, v[130:131]
	ds_read_b128 v[182:185], v153 offset:32768
	ds_read_b128 v[186:189], v153 offset:33792
	ds_read_b128 v[190:193], v153 offset:34816
	ds_read_b128 v[202:205], v153 offset:35840
	ds_read_b128 v[206:209], v153 offset:36864
	ds_read_b128 v[210:213], v153 offset:37888
	ds_read_b128 v[214:217], v153 offset:38912
	ds_read_b128 v[218:221], v153 offset:39936
	global_load_lds_dwordx4 v[230:231], off
	v_lshl_add_u64 v[230:231], s[12:13], 0, v[134:135]
	s_mov_b32 m0, s84
	s_nop 0
	global_load_lds_dwordx4 v[230:231], off
	s_waitcnt vmcnt(8)
	s_waitcnt lgkmcnt(0)
	s_barrier
	s_setprio 1
	v_mfma_f32_16x16x32_bf16 v[126:129], v[144:147], v[182:185], v[126:129]
	v_mfma_f32_16x16x32_bf16 v[122:125], v[158:161], v[182:185], v[122:125]
	v_mfma_f32_16x16x32_bf16 v[110:113], v[144:147], v[190:193], v[110:113]
	v_mfma_f32_16x16x32_bf16 v[106:109], v[158:161], v[190:193], v[106:109]
	v_mfma_f32_16x16x32_bf16 v[92:95], v[144:147], v[206:209], v[92:95]
	v_mfma_f32_16x16x32_bf16 v[88:91], v[158:161], v[206:209], v[88:91]
	v_mfma_f32_16x16x32_bf16 v[76:79], v[144:147], v[214:217], v[76:79]
	v_mfma_f32_16x16x32_bf16 v[72:75], v[158:161], v[214:217], v[72:75]
	v_mfma_f32_16x16x32_bf16 v[126:129], v[154:157], v[186:189], v[126:129]
	v_mfma_f32_16x16x32_bf16 v[122:125], v[162:165], v[186:189], v[122:125]
	v_mfma_f32_16x16x32_bf16 v[110:113], v[154:157], v[202:205], v[110:113]
	v_mfma_f32_16x16x32_bf16 v[106:109], v[162:165], v[202:205], v[106:109]
	v_mfma_f32_16x16x32_bf16 v[92:95], v[154:157], v[210:213], v[92:95]
	v_mfma_f32_16x16x32_bf16 v[88:91], v[162:165], v[210:213], v[88:91]
	v_mfma_f32_16x16x32_bf16 v[76:79], v[154:157], v[218:221], v[76:79]
	v_mfma_f32_16x16x32_bf16 v[72:75], v[162:165], v[218:221], v[72:75]
	s_setprio 0
	s_setprio 1
	v_mfma_f32_16x16x32_bf16 v[118:121], v[166:169], v[182:185], v[118:121]
	v_mfma_f32_16x16x32_bf16 v[114:117], v[174:177], v[182:185], v[114:117]
	v_mfma_f32_16x16x32_bf16 v[102:105], v[166:169], v[190:193], v[102:105]
	v_mfma_f32_16x16x32_bf16 v[98:101], v[174:177], v[190:193], v[98:101]
	v_mfma_f32_16x16x32_bf16 v[84:87], v[166:169], v[206:209], v[84:87]
	v_mfma_f32_16x16x32_bf16 v[80:83], v[174:177], v[206:209], v[80:83]
	v_mfma_f32_16x16x32_bf16 v[68:71], v[166:169], v[214:217], v[68:71]
	v_mfma_f32_16x16x32_bf16 v[64:67], v[174:177], v[214:217], v[64:67]
	v_mfma_f32_16x16x32_bf16 v[118:121], v[170:173], v[186:189], v[118:121]
	v_mfma_f32_16x16x32_bf16 v[114:117], v[178:181], v[186:189], v[114:117]
	v_mfma_f32_16x16x32_bf16 v[102:105], v[170:173], v[202:205], v[102:105]
	v_mfma_f32_16x16x32_bf16 v[98:101], v[178:181], v[202:205], v[98:101]
	v_mfma_f32_16x16x32_bf16 v[84:87], v[170:173], v[210:213], v[84:87]
	v_mfma_f32_16x16x32_bf16 v[80:83], v[178:181], v[210:213], v[80:83]
	v_mfma_f32_16x16x32_bf16 v[68:71], v[170:173], v[218:221], v[68:71]
	v_mfma_f32_16x16x32_bf16 v[64:67], v[178:181], v[218:221], v[64:67]
	s_setprio 0
	s_barrier
; #define PG8_STAGE(bufoff, gbase, voff) do { _Pragma("unroll") for (int _i = 0; _i < 2; ++_i) \
;         __builtin_amdgcn_global_load_lds((const unsigned*)((const char*)(gbase) + (voff)[_i]), (PG8_LAS unsigned*)(lds + (bufoff) + ldsw + _i * 8192), 16, 0, 0); } while (0)
; #define PG8_LDA(dst, b, h) do { _Pragma("unroll") for (int m = 0; m < 4; ++m) _Pragma("unroll") for (int k = 0; k < 2; ++k) dst[m][k] = *(const PG8_LAS bf16x8*)(lds + PG8_SA(b, h) + aoff + m * 2048 + k * 1024); } while (0)
; #define PG8_MMA(ai, bj, At, Bt) do { __builtin_amdgcn_s_setprio(1); _Pragma("unroll") for (int m = 0; m < 4; ++m) _Pragma("unroll") for (int n = 0; n < 2; ++n) _Pragma("unroll") for (int k = 0; k < 2; ++k) \
;         acc[ai][bj][m][n] = __builtin_amdgcn_mfma_f32_16x16x32_bf16(Bt[n][k], At[m][k], acc[ai][bj][m][n], 0, 0, 0); __builtin_amdgcn_s_setprio(0); } while (0)
; #define PG8_WAIT_V(n) asm volatile("s_waitcnt vmcnt(" #n ")" ::: "memory")
; #define PG8_WAIT_L(n) asm volatile("s_waitcnt lgkmcnt(" #n ")" ::: "memory")
; #define PG8_BAR __builtin_amdgcn_s_barrier()
; #define PG8_SCHED __builtin_amdgcn_sched_barrier(0)
; template <class Epi, class Sched, bool ALIGN_EPI = false, bool SP2 = false>
; __device__ __forceinline__ void gemm_phase(PG8_LAS unsigned char* lds, const Gemm g, const Sched& S, const Epi& E) {
;     ...
;         for (int t = 0; t < nt; t += 2) {
;             const bool last = (t == nt - 2);
;     ...
;             PG8_LDA(At, 1, 1); PG8_STAGE(PG8_SB(1, 0), b3, voffB); PG8_STAGE(PG8_SB(1, 1), b3 + hstep, voffB); PG8_STAGE(PG8_SA(1, 0), a3, voffA);
;             PG8_WAIT_V(8); PG8_WAIT_L(0); PG8_BAR; PG8_MMA(1, 0, At, B0); PG8_MMA(1, 1, At, B1); PG8_BAR; PG8_SCHED;
	s_add_i32 s12, vcc_lo, s70
	v_lshl_add_u64 v[222:223], v[222:223], 0, s[36:37]
	s_mov_b32 m0, s12
	ds_read_b128 v[182:185], v153 offset:49152
	ds_read_b128 v[186:189], v153 offset:50176
	ds_read_b128 v[190:193], v153 offset:51200
	ds_read_b128 v[202:205], v153 offset:52224
	ds_read_b128 v[206:209], v153 offset:53248
	ds_read_b128 v[210:213], v153 offset:54272
	ds_read_b128 v[214:217], v153 offset:55296
	ds_read_b128 v[218:221], v153 offset:56320
	global_load_lds_dwordx4 v[222:223], off
	s_add_i32 m0, s12, 0x2000
	s_add_u32 s12, s62, 0x80080
	v_lshl_add_u64 v[222:223], v[224:225], 0, s[36:37]
	s_addc_u32 s13, s63, 0
	s_add_i32 s62, vcc_hi, s70
	global_load_lds_dwordx4 v[222:223], off
	v_lshl_add_u64 v[222:223], s[12:13], 0, v[132:133]
	s_mov_b32 m0, s62
	s_nop 0
	global_load_lds_dwordx4 v[222:223], off
	v_lshl_add_u64 v[222:223], s[12:13], 0, v[136:137]
	s_add_i32 m0, s62, 0x2000
	s_nop 0
	global_load_lds_dwordx4 v[222:223], off
	v_lshl_add_u64 v[222:223], v[226:227], 0, s[36:37]
	s_mov_b32 m0, s85
	s_nop 0
	global_load_lds_dwordx4 v[222:223], off
	v_lshl_add_u64 v[222:223], v[228:229], 0, s[36:37]
	s_mov_b32 m0, s92
	s_nop 0
	global_load_lds_dwordx4 v[222:223], off
	s_waitcnt vmcnt(8)
	s_waitcnt lgkmcnt(0)
	s_barrier
	s_setprio 1
	v_mfma_f32_16x16x32_bf16 v[60:63], v[144:147], v[182:185], v[60:63]
	v_mfma_f32_16x16x32_bf16 v[56:59], v[158:161], v[182:185], v[56:59]
	v_mfma_f32_16x16x32_bf16 v[44:47], v[144:147], v[190:193], v[44:47]
	v_mfma_f32_16x16x32_bf16 v[40:43], v[158:161], v[190:193], v[40:43]
	v_mfma_f32_16x16x32_bf16 v[28:31], v[144:147], v[206:209], v[28:31]
	v_mfma_f32_16x16x32_bf16 v[24:27], v[158:161], v[206:209], v[24:27]
	v_mfma_f32_16x16x32_bf16 v[12:15], v[144:147], v[214:217], v[12:15]
	v_mfma_f32_16x16x32_bf16 v[8:11], v[158:161], v[214:217], v[8:11]
	v_mfma_f32_16x16x32_bf16 v[60:63], v[154:157], v[186:189], v[60:63]
	v_mfma_f32_16x16x32_bf16 v[56:59], v[162:165], v[186:189], v[56:59]
	v_mfma_f32_16x16x32_bf16 v[44:47], v[154:157], v[202:205], v[44:47]
	v_mfma_f32_16x16x32_bf16 v[40:43], v[162:165], v[202:205], v[40:43]
	v_mfma_f32_16x16x32_bf16 v[28:31], v[154:157], v[210:213], v[28:31]
	v_mfma_f32_16x16x32_bf16 v[24:27], v[162:165], v[210:213], v[24:27]
	v_mfma_f32_16x16x32_bf16 v[12:15], v[154:157], v[218:221], v[12:15]
	v_mfma_f32_16x16x32_bf16 v[8:11], v[162:165], v[218:221], v[8:11]
	s_setprio 0
	s_setprio 1
	v_mfma_f32_16x16x32_bf16 v[52:55], v[166:169], v[182:185], v[52:55]
	v_mfma_f32_16x16x32_bf16 v[48:51], v[174:177], v[182:185], v[48:51]
	v_mfma_f32_16x16x32_bf16 v[36:39], v[166:169], v[190:193], v[36:39]
	v_mfma_f32_16x16x32_bf16 v[32:35], v[174:177], v[190:193], v[32:35]
	v_mfma_f32_16x16x32_bf16 v[20:23], v[166:169], v[206:209], v[20:23]
	v_mfma_f32_16x16x32_bf16 v[16:19], v[174:177], v[206:209], v[16:19]
	v_mfma_f32_16x16x32_bf16 v[4:7], v[166:169], v[214:217], v[4:7]
	v_mfma_f32_16x16x32_bf16 v[0:3], v[174:177], v[214:217], v[0:3]
	v_mfma_f32_16x16x32_bf16 v[52:55], v[170:173], v[186:189], v[52:55]
	v_mfma_f32_16x16x32_bf16 v[48:51], v[178:181], v[186:189], v[48:51]
	v_mfma_f32_16x16x32_bf16 v[36:39], v[170:173], v[202:205], v[36:39]
	v_mfma_f32_16x16x32_bf16 v[32:35], v[178:181], v[202:205], v[32:35]
	v_mfma_f32_16x16x32_bf16 v[20:23], v[170:173], v[210:213], v[20:23]
	v_mfma_f32_16x16x32_bf16 v[16:19], v[178:181], v[210:213], v[16:19]
	v_mfma_f32_16x16x32_bf16 v[4:7], v[170:173], v[218:221], v[4:7]
	v_mfma_f32_16x16x32_bf16 v[0:3], v[178:181], v[218:221], v[0:3]
	s_setprio 0
	s_barrier
	s_add_i32 s55, s55, 2
	s_add_u32 s18, s18, 0x100
	s_addc_u32 s19, s19, 0
	s_add_u32 s42, s42, 0x100
	s_addc_u32 s43, s43, 0
	s_cmp_gt_u32 s55, 29
	s_cbranch_scc0 .LBB0_175
	s_and_b64 vcc, exec, s[0:1]
	s_cbranch_vccz .LBB0_178
	s_barrier

; #define PG8_STAGE(bufoff, gbase, voff) do { _Pragma("unroll") for (int _i = 0; _i < 2; ++_i) \
;         __builtin_amdgcn_global_load_lds((const unsigned*)((const char*)(gbase) + (voff)[_i]), (PG8_LAS unsigned*)(lds + (bufoff) + ldsw + _i * 8192), 16, 0, 0); } while (0)
; #define PG8_LDA(dst, b, h) do { _Pragma("unroll") for (int m = 0; m < 4; ++m) _Pragma("unroll") for (int k = 0; k < 2; ++k) dst[m][k] = *(const PG8_LAS bf16x8*)(lds + PG8_SA(b, h) + aoff + m * 2048 + k * 1024); } while (0)
; #define PG8_LDB(dst, b, h) do { _Pragma("unroll") for (int n = 0; n < 2; ++n) _Pragma("unroll") for (int k = 0; k < 2; ++k) dst[n][k] = *(const PG8_LAS bf16x8*)(lds + PG8_SB(b, h) + boff + n * 2048 + k * 1024); } while (0)
; #define PG8_MMA(ai, bj, At, Bt) do { __builtin_amdgcn_s_setprio(1); _Pragma("unroll") for (int m = 0; m < 4; ++m) _Pragma("unroll") for (int n = 0; n < 2; ++n) _Pragma("unroll") for (int k = 0; k < 2; ++k) \
;         acc[ai][bj][m][n] = __builtin_amdgcn_mfma_f32_16x16x32_bf16(Bt[n][k], At[m][k], acc[ai][bj][m][n], 0, 0, 0); __builtin_amdgcn_s_setprio(0); } while (0)
; #define PG8_WAIT_V(n) asm volatile("s_waitcnt vmcnt(" #n ")" ::: "memory")
; #define PG8_BAR __builtin_amdgcn_s_barrier()
; template <class Epi, class Sched, bool ALIGN_EPI = false, bool SP2 = false>
; __device__ __forceinline__ void gemm_phase(PG8_LAS unsigned char* lds, const Gemm g, const Sched& S, const Epi& E) {
;     ...
;         for (int t = 0; t < nt; t += 2) {
;             const bool last = (t == nt - 2);
;             const char* a1 = cA + (size_t)(t + 1) * kstep;
;             const char* a2 = last ? nA : cA + (size_t)(t + 2) * kstep; const char* b2 = last ? nB : cB + (size_t)(t + 2) * kstep;
;             const char* a3 = a2 + kstep; const char* b3 = b2 + kstep;
;             if (last && has_next) S.a_ready(nxt);
;             if constexpr (SP2) {
;             PG8_LDB(B0, 0, 0); PG8_LDB(B1, 0, 1); PG8_SCHED; PG8_LDA(At, 0, 0); PG8_STAGE(PG8_SA(1, 1), a1 + hstep, voffA);
;             PG8_WAIT_V(8); PG8_WAIT_L(0); PG8_BAR; PG8_MMA(0, 0, At, B0); PG8_MMA(0, 1, At, B1); PG8_BAR; PG8_SCHED;
;             PG8_LDA(At, 0, 1); PG8_STAGE(PG8_SB(0, 0), b2, voffB); PG8_STAGE(PG8_SB(0, 1), b2 + hstep, voffB); PG8_STAGE(PG8_SA(0, 0), a2, voffA);
;             PG8_WAIT_V(8); PG8_WAIT_L(0); PG8_BAR; PG8_MMA(1, 0, At, B0); PG8_MMA(1, 1, At, B1); PG8_BAR; PG8_SCHED;
.LBB0_236:
	s_add_u32 s12, s42, 0xfff80080
	s_addc_u32 s13, s43, -1
	s_add_i32 s73, 0, 0x10000
	s_cmp_eq_u32 s51, 28
	s_cselect_b32 s61, s10, s13
	s_cselect_b32 s60, s11, s12
	v_add_u32_e32 v148, s73, v149
	s_cselect_b32 s59, s5, s19
	s_cselect_b32 s58, s15, s18
	s_add_i32 s84, 0, 0x14000
	ds_read_b128 v[144:147], v148
	ds_read_b128 v[154:157], v148 offset:1024
	ds_read_b128 v[158:161], v148 offset:2048
	ds_read_b128 v[162:165], v148 offset:3072
	v_add_u32_e32 v148, s84, v149
	ds_read_b128 v[166:169], v148
	ds_read_b128 v[170:173], v148 offset:1024
	ds_read_b128 v[174:177], v148 offset:2048
	ds_read_b128 v[178:181], v148 offset:3072
	v_lshl_add_u64 v[222:223], s[42:43], 0, v[142:143]
	s_add_i32 m0, s57, 0xc000
	ds_read_b128 v[182:185], v152
	ds_read_b128 v[186:189], v152 offset:1024
	ds_read_b128 v[190:193], v152 offset:2048
	ds_read_b128 v[202:205], v152 offset:3072
	ds_read_b128 v[206:209], v152 offset:4096
	ds_read_b128 v[210:213], v152 offset:5120
	ds_read_b128 v[214:217], v152 offset:6144
	ds_read_b128 v[218:221], v152 offset:7168
	global_load_lds_dwordx4 v[222:223], off
	v_lshl_add_u64 v[222:223], s[42:43], 0, v[140:141]
	s_add_i32 m0, s57, 0xe000
	s_nop 0
	global_load_lds_dwordx4 v[222:223], off
	s_waitcnt vmcnt(8)
	s_waitcnt lgkmcnt(0)
	s_barrier
	s_setprio 1
	v_mfma_f32_16x16x32_bf16 v[126:129], v[144:147], v[182:185], v[126:129]
	v_mfma_f32_16x16x32_bf16 v[122:125], v[158:161], v[182:185], v[122:125]
	v_mfma_f32_16x16x32_bf16 v[110:113], v[144:147], v[190:193], v[110:113]
	v_mfma_f32_16x16x32_bf16 v[106:109], v[158:161], v[190:193], v[106:109]
	v_mfma_f32_16x16x32_bf16 v[92:95], v[144:147], v[206:209], v[92:95]
	v_mfma_f32_16x16x32_bf16 v[88:91], v[158:161], v[206:209], v[88:91]
	v_mfma_f32_16x16x32_bf16 v[76:79], v[144:147], v[214:217], v[76:79]
	v_mfma_f32_16x16x32_bf16 v[72:75], v[158:161], v[214:217], v[72:75]
	v_mfma_f32_16x16x32_bf16 v[126:129], v[154:157], v[186:189], v[126:129]
	v_mfma_f32_16x16x32_bf16 v[122:125], v[162:165], v[186:189], v[122:125]
	v_mfma_f32_16x16x32_bf16 v[110:113], v[154:157], v[202:205], v[110:113]
	v_mfma_f32_16x16x32_bf16 v[106:109], v[162:165], v[202:205], v[106:109]
	v_mfma_f32_16x16x32_bf16 v[92:95], v[154:157], v[210:213], v[92:95]
	v_mfma_f32_16x16x32_bf16 v[88:91], v[162:165], v[210:213], v[88:91]
	v_mfma_f32_16x16x32_bf16 v[76:79], v[154:157], v[218:221], v[76:79]
	v_mfma_f32_16x16x32_bf16 v[72:75], v[162:165], v[218:221], v[72:75]
	s_setprio 0
	s_setprio 1
	v_mfma_f32_16x16x32_bf16 v[118:121], v[166:169], v[182:185], v[118:121]
	v_mfma_f32_16x16x32_bf16 v[114:117], v[174:177], v[182:185], v[114:117]
	v_mfma_f32_16x16x32_bf16 v[102:105], v[166:169], v[190:193], v[102:105]
	v_mfma_f32_16x16x32_bf16 v[98:101], v[174:177], v[190:193], v[98:101]
	v_mfma_f32_16x16x32_bf16 v[84:87], v[166:169], v[206:209], v[84:87]
	v_mfma_f32_16x16x32_bf16 v[80:83], v[174:177], v[206:209], v[80:83]
	v_mfma_f32_16x16x32_bf16 v[68:71], v[166:169], v[214:217], v[68:71]
	v_mfma_f32_16x16x32_bf16 v[64:67], v[174:177], v[214:217], v[64:67]
	v_mfma_f32_16x16x32_bf16 v[118:121], v[170:173], v[186:189], v[118:121]
	v_mfma_f32_16x16x32_bf16 v[114:117], v[178:181], v[186:189], v[114:117]
	v_mfma_f32_16x16x32_bf16 v[102:105], v[170:173], v[202:205], v[102:105]
	v_mfma_f32_16x16x32_bf16 v[98:101], v[178:181], v[202:205], v[98:101]
	v_mfma_f32_16x16x32_bf16 v[84:87], v[170:173], v[210:213], v[84:87]
	v_mfma_f32_16x16x32_bf16 v[80:83], v[178:181], v[210:213], v[80:83]
	v_mfma_f32_16x16x32_bf16 v[68:71], v[170:173], v[218:221], v[68:71]
	v_mfma_f32_16x16x32_bf16 v[64:67], v[178:181], v[218:221], v[64:67]
	s_setprio 0
	s_barrier
	s_add_i32 s12, s73, s9
	v_lshl_add_u64 v[222:223], s[58:59], 0, v[132:133]
	s_mov_b32 m0, s12
	ds_read_b128 v[182:185], v152 offset:16384
	ds_read_b128 v[186:189], v152 offset:17408
	ds_read_b128 v[190:193], v152 offset:18432
	ds_read_b128 v[202:205], v152 offset:19456
	ds_read_b128 v[206:209], v152 offset:20480
	ds_read_b128 v[210:213], v152 offset:21504
	ds_read_b128 v[214:217], v152 offset:22528
	ds_read_b128 v[218:221], v152 offset:23552
	global_load_lds_dwordx4 v[222:223], off
	s_add_i32 m0, s12, 0x2000
	s_add_u32 s12, s58, 0x80000
	v_lshl_add_u64 v[224:225], s[58:59], 0, v[136:137]
	s_addc_u32 s13, s59, 0
	s_add_i32 s73, s84, s9
	global_load_lds_dwordx4 v[224:225], off
	v_lshl_add_u64 v[226:227], s[12:13], 0, v[132:133]
	s_mov_b32 m0, s73
	v_lshl_add_u64 v[228:229], s[60:61], 0, v[134:135]
	global_load_lds_dwordx4 v[226:227], off
	v_lshl_add_u64 v[226:227], s[12:13], 0, v[136:137]
	s_add_i32 m0, s73, 0x2000
	s_nop 0
	global_load_lds_dwordx4 v[226:227], off
	v_lshl_add_u64 v[226:227], s[60:61], 0, v[130:131]
	s_mov_b32 m0, s57
	s_nop 0
	global_load_lds_dwordx4 v[226:227], off
	s_mov_b32 m0, s63
	s_nop 0
	global_load_lds_dwordx4 v[228:229], off
	s_waitcnt vmcnt(8)
	s_waitcnt lgkmcnt(0)
	s_barrier
; #define PG8_STAGE(bufoff, gbase, voff) do { _Pragma("unroll") for (int _i = 0; _i < 2; ++_i) \
;         __builtin_amdgcn_global_load_lds((const unsigned*)((const char*)(gbase) + (voff)[_i]), (PG8_LAS unsigned*)(lds + (bufoff) + ldsw + _i * 8192), 16, 0, 0); } while (0)
; #define PG8_LDA(dst, b, h) do { _Pragma("unroll") for (int m = 0; m < 4; ++m) _Pragma("unroll") for (int k = 0; k < 2; ++k) dst[m][k] = *(const PG8_LAS bf16x8*)(lds + PG8_SA(b, h) + aoff + m * 2048 + k * 1024); } while (0)
; #define PG8_LDB(dst, b, h) do { _Pragma("unroll") for (int n = 0; n < 2; ++n) _Pragma("unroll") for (int k = 0; k < 2; ++k) dst[n][k] = *(const PG8_LAS bf16x8*)(lds + PG8_SB(b, h) + boff + n * 2048 + k * 1024); } while (0)
; #define PG8_MMA(ai, bj, At, Bt) do { __builtin_amdgcn_s_setprio(1); _Pragma("unroll") for (int m = 0; m < 4; ++m) _Pragma("unroll") for (int n = 0; n < 2; ++n) _Pragma("unroll") for (int k = 0; k < 2; ++k) \
;         acc[ai][bj][m][n] = __builtin_amdgcn_mfma_f32_16x16x32_bf16(Bt[n][k], At[m][k], acc[ai][bj][m][n], 0, 0, 0); __builtin_amdgcn_s_setprio(0); } while (0)
; #define PG8_WAIT_V(n) asm volatile("s_waitcnt vmcnt(" #n ")" ::: "memory")
; #define PG8_WAIT_L(n) asm volatile("s_waitcnt lgkmcnt(" #n ")" ::: "memory")
; #define PG8_BAR __builtin_amdgcn_s_barrier()
; #define PG8_SCHED __builtin_amdgcn_sched_barrier(0)
; template <class Epi, class Sched, bool ALIGN_EPI = false, bool SP2 = false>
; __device__ __forceinline__ void gemm_phase(PG8_LAS unsigned char* lds, const Gemm g, const Sched& S, const Epi& E) {
;     ...
;             PG8_WAIT_V(8); PG8_WAIT_L(0); PG8_BAR; PG8_MMA(1, 0, At, B0); PG8_MMA(1, 1, At, B1); PG8_BAR; PG8_SCHED;
;             PG8_LDB(B0, 1, 0); PG8_LDB(B1, 1, 1); PG8_SCHED; PG8_LDA(At, 1, 0); PG8_STAGE(PG8_SA(0, 1), a2 + hstep, voffA);
;             PG8_WAIT_V(8); PG8_WAIT_L(0); PG8_BAR; PG8_MMA(0, 0, At, B0); PG8_MMA(0, 1, At, B1); PG8_BAR; PG8_SCHED;
	s_setprio 1
	v_mfma_f32_16x16x32_bf16 v[60:63], v[144:147], v[182:185], v[60:63]
	v_mfma_f32_16x16x32_bf16 v[56:59], v[158:161], v[182:185], v[56:59]
	v_mfma_f32_16x16x32_bf16 v[44:47], v[144:147], v[190:193], v[44:47]
	v_mfma_f32_16x16x32_bf16 v[40:43], v[158:161], v[190:193], v[40:43]
	v_mfma_f32_16x16x32_bf16 v[28:31], v[144:147], v[206:209], v[28:31]
	v_mfma_f32_16x16x32_bf16 v[24:27], v[158:161], v[206:209], v[24:27]
	v_mfma_f32_16x16x32_bf16 v[12:15], v[144:147], v[214:217], v[12:15]
	v_mfma_f32_16x16x32_bf16 v[8:11], v[158:161], v[214:217], v[8:11]
	v_mfma_f32_16x16x32_bf16 v[60:63], v[154:157], v[186:189], v[60:63]
	v_mfma_f32_16x16x32_bf16 v[56:59], v[162:165], v[186:189], v[56:59]
	v_mfma_f32_16x16x32_bf16 v[44:47], v[154:157], v[202:205], v[44:47]
	v_mfma_f32_16x16x32_bf16 v[40:43], v[162:165], v[202:205], v[40:43]
	v_mfma_f32_16x16x32_bf16 v[28:31], v[154:157], v[210:213], v[28:31]
	v_mfma_f32_16x16x32_bf16 v[24:27], v[162:165], v[210:213], v[24:27]
	v_mfma_f32_16x16x32_bf16 v[12:15], v[154:157], v[218:221], v[12:15]
	v_mfma_f32_16x16x32_bf16 v[8:11], v[162:165], v[218:221], v[8:11]
	s_setprio 0
	s_setprio 1
	v_mfma_f32_16x16x32_bf16 v[52:55], v[166:169], v[182:185], v[52:55]
	v_mfma_f32_16x16x32_bf16 v[48:51], v[174:177], v[182:185], v[48:51]
	v_mfma_f32_16x16x32_bf16 v[36:39], v[166:169], v[190:193], v[36:39]
	v_mfma_f32_16x16x32_bf16 v[32:35], v[174:177], v[190:193], v[32:35]
	v_mfma_f32_16x16x32_bf16 v[20:23], v[166:169], v[206:209], v[20:23]
	v_mfma_f32_16x16x32_bf16 v[16:19], v[174:177], v[206:209], v[16:19]
	v_mfma_f32_16x16x32_bf16 v[4:7], v[166:169], v[214:217], v[4:7]
	v_mfma_f32_16x16x32_bf16 v[0:3], v[174:177], v[214:217], v[0:3]
	v_mfma_f32_16x16x32_bf16 v[52:55], v[170:173], v[186:189], v[52:55]
	v_mfma_f32_16x16x32_bf16 v[48:51], v[178:181], v[186:189], v[48:51]
	v_mfma_f32_16x16x32_bf16 v[36:39], v[170:173], v[202:205], v[36:39]
	v_mfma_f32_16x16x32_bf16 v[32:35], v[178:181], v[202:205], v[32:35]
	v_mfma_f32_16x16x32_bf16 v[20:23], v[170:173], v[210:213], v[20:23]
	v_mfma_f32_16x16x32_bf16 v[16:19], v[178:181], v[210:213], v[16:19]
	v_mfma_f32_16x16x32_bf16 v[4:7], v[170:173], v[218:221], v[4:7]
	v_mfma_f32_16x16x32_bf16 v[0:3], v[178:181], v[218:221], v[0:3]
	s_setprio 0
	s_barrier
	s_add_i32 s73, 0, 0x18000
	v_add_u32_e32 v148, s73, v149
	s_add_i32 s84, 0, 0x1c000
	ds_read_b128 v[144:147], v148
	ds_read_b128 v[154:157], v148 offset:1024
	ds_read_b128 v[158:161], v148 offset:2048
	ds_read_b128 v[162:165], v148 offset:3072
	v_add_u32_e32 v148, s84, v149
	ds_read_b128 v[166:169], v148
	ds_read_b128 v[170:173], v148 offset:1024
	ds_read_b128 v[174:177], v148 offset:2048
	ds_read_b128 v[178:181], v148 offset:3072
	s_add_u32 s12, s60, 0x80000
	s_addc_u32 s13, s61, 0
	s_mov_b32 m0, s64
	v_lshl_add_u64 v[230:231], s[12:13], 0, v[130:131]
	ds_read_b128 v[182:185], v152 offset:32768
	ds_read_b128 v[186:189], v152 offset:33792
	ds_read_b128 v[190:193], v152 offset:34816
	ds_read_b128 v[202:205], v152 offset:35840
	ds_read_b128 v[206:209], v152 offset:36864
	ds_read_b128 v[210:213], v152 offset:37888
	ds_read_b128 v[214:217], v152 offset:38912
	ds_read_b128 v[218:221], v152 offset:39936
	global_load_lds_dwordx4 v[230:231], off
	v_lshl_add_u64 v[230:231], s[12:13], 0, v[134:135]
	s_mov_b32 m0, s65
	s_nop 0
	global_load_lds_dwordx4 v[230:231], off
	s_waitcnt vmcnt(8)
	s_waitcnt lgkmcnt(0)
	s_barrier
	s_setprio 1
	v_mfma_f32_16x16x32_bf16 v[126:129], v[144:147], v[182:185], v[126:129]
	v_mfma_f32_16x16x32_bf16 v[122:125], v[158:161], v[182:185], v[122:125]
	v_mfma_f32_16x16x32_bf16 v[110:113], v[144:147], v[190:193], v[110:113]
	v_mfma_f32_16x16x32_bf16 v[106:109], v[158:161], v[190:193], v[106:109]
	v_mfma_f32_16x16x32_bf16 v[92:95], v[144:147], v[206:209], v[92:95]
	v_mfma_f32_16x16x32_bf16 v[88:91], v[158:161], v[206:209], v[88:91]
	v_mfma_f32_16x16x32_bf16 v[76:79], v[144:147], v[214:217], v[76:79]
	v_mfma_f32_16x16x32_bf16 v[72:75], v[158:161], v[214:217], v[72:75]
	v_mfma_f32_16x16x32_bf16 v[126:129], v[154:157], v[186:189], v[126:129]
	v_mfma_f32_16x16x32_bf16 v[122:125], v[162:165], v[186:189], v[122:125]
	v_mfma_f32_16x16x32_bf16 v[110:113], v[154:157], v[202:205], v[110:113]
	v_mfma_f32_16x16x32_bf16 v[106:109], v[162:165], v[202:205], v[106:109]
	v_mfma_f32_16x16x32_bf16 v[92:95], v[154:157], v[210:213], v[92:95]
	v_mfma_f32_16x16x32_bf16 v[88:91], v[162:165], v[210:213], v[88:91]
	v_mfma_f32_16x16x32_bf16 v[76:79], v[154:157], v[218:221], v[76:79]
	v_mfma_f32_16x16x32_bf16 v[72:75], v[162:165], v[218:221], v[72:75]
	s_setprio 0
	s_setprio 1
	v_mfma_f32_16x16x32_bf16 v[118:121], v[166:169], v[182:185], v[118:121]
	v_mfma_f32_16x16x32_bf16 v[114:117], v[174:177], v[182:185], v[114:117]
	v_mfma_f32_16x16x32_bf16 v[102:105], v[166:169], v[190:193], v[102:105]
	v_mfma_f32_16x16x32_bf16 v[98:101], v[174:177], v[190:193], v[98:101]
	v_mfma_f32_16x16x32_bf16 v[84:87], v[166:169], v[206:209], v[84:87]
	v_mfma_f32_16x16x32_bf16 v[80:83], v[174:177], v[206:209], v[80:83]
	v_mfma_f32_16x16x32_bf16 v[68:71], v[166:169], v[214:217], v[68:71]
	v_mfma_f32_16x16x32_bf16 v[64:67], v[174:177], v[214:217], v[64:67]
	v_mfma_f32_16x16x32_bf16 v[118:121], v[170:173], v[186:189], v[118:121]
	v_mfma_f32_16x16x32_bf16 v[114:117], v[178:181], v[186:189], v[114:117]
	v_mfma_f32_16x16x32_bf16 v[102:105], v[170:173], v[202:205], v[102:105]
	v_mfma_f32_16x16x32_bf16 v[98:101], v[178:181], v[202:205], v[98:101]
	v_mfma_f32_16x16x32_bf16 v[84:87], v[170:173], v[210:213], v[84:87]
	v_mfma_f32_16x16x32_bf16 v[80:83], v[178:181], v[210:213], v[80:83]
	v_mfma_f32_16x16x32_bf16 v[68:71], v[170:173], v[218:221], v[68:71]
	v_mfma_f32_16x16x32_bf16 v[64:67], v[178:181], v[218:221], v[64:67]
	s_setprio 0
	s_barrier
; #define PG8_STAGE(bufoff, gbase, voff) do { _Pragma("unroll") for (int _i = 0; _i < 2; ++_i) \
;         __builtin_amdgcn_global_load_lds((const unsigned*)((const char*)(gbase) + (voff)[_i]), (PG8_LAS unsigned*)(lds + (bufoff) + ldsw + _i * 8192), 16, 0, 0); } while (0)
; #define PG8_LDA(dst, b, h) do { _Pragma("unroll") for (int m = 0; m < 4; ++m) _Pragma("unroll") for (int k = 0; k < 2; ++k) dst[m][k] = *(const PG8_LAS bf16x8*)(lds + PG8_SA(b, h) + aoff + m * 2048 + k * 1024); } while (0)
; #define PG8_MMA(ai, bj, At, Bt) do { __builtin_amdgcn_s_setprio(1); _Pragma("unroll") for (int m = 0; m < 4; ++m) _Pragma("unroll") for (int n = 0; n < 2; ++n) _Pragma("unroll") for (int k = 0; k < 2; ++k) \
;         acc[ai][bj][m][n] = __builtin_amdgcn_mfma_f32_16x16x32_bf16(Bt[n][k], At[m][k], acc[ai][bj][m][n], 0, 0, 0); __builtin_amdgcn_s_setprio(0); } while (0)
; #define PG8_WAIT_V(n) asm volatile("s_waitcnt vmcnt(" #n ")" ::: "memory")
; #define PG8_WAIT_L(n) asm volatile("s_waitcnt lgkmcnt(" #n ")" ::: "memory")
; #define PG8_BAR __builtin_amdgcn_s_barrier()
; #define PG8_SCHED __builtin_amdgcn_sched_barrier(0)
; template <class Epi, class Sched, bool ALIGN_EPI = false, bool SP2 = false>
; __device__ __forceinline__ void gemm_phase(PG8_LAS unsigned char* lds, const Gemm g, const Sched& S, const Epi& E) {
;     ...
;         for (int t = 0; t < nt; t += 2) {
;             const bool last = (t == nt - 2);
;     ...
;             PG8_LDA(At, 1, 1); PG8_STAGE(PG8_SB(1, 0), b3, voffB); PG8_STAGE(PG8_SB(1, 1), b3 + hstep, voffB); PG8_STAGE(PG8_SA(1, 0), a3, voffA);
;             PG8_WAIT_V(8); PG8_WAIT_L(0); PG8_BAR; PG8_MMA(1, 0, At, B0); PG8_MMA(1, 1, At, B1); PG8_BAR; PG8_SCHED;
	s_add_i32 s12, s73, s9
	v_lshl_add_u64 v[222:223], v[222:223], 0, s[36:37]
	s_mov_b32 m0, s12
	ds_read_b128 v[182:185], v152 offset:49152
	ds_read_b128 v[186:189], v152 offset:50176
	ds_read_b128 v[190:193], v152 offset:51200
	ds_read_b128 v[202:205], v152 offset:52224
	ds_read_b128 v[206:209], v152 offset:53248
	ds_read_b128 v[210:213], v152 offset:54272
	ds_read_b128 v[214:217], v152 offset:55296
	ds_read_b128 v[218:221], v152 offset:56320
	global_load_lds_dwordx4 v[222:223], off
	s_add_i32 m0, s12, 0x2000
	s_add_u32 s12, s58, 0x80080
	v_lshl_add_u64 v[222:223], v[224:225], 0, s[36:37]
	s_addc_u32 s13, s59, 0
	s_add_i32 s58, s84, s9
	global_load_lds_dwordx4 v[222:223], off
	v_lshl_add_u64 v[222:223], s[12:13], 0, v[132:133]
	s_mov_b32 m0, s58
	s_nop 0
	global_load_lds_dwordx4 v[222:223], off
	v_lshl_add_u64 v[222:223], s[12:13], 0, v[136:137]
	s_add_i32 m0, s58, 0x2000
	s_nop 0
	global_load_lds_dwordx4 v[222:223], off
	v_lshl_add_u64 v[222:223], v[226:227], 0, s[36:37]
	s_mov_b32 m0, s70
	s_nop 0
	global_load_lds_dwordx4 v[222:223], off
	v_lshl_add_u64 v[222:223], v[228:229], 0, s[36:37]
	s_mov_b32 m0, s71
	s_nop 0
	global_load_lds_dwordx4 v[222:223], off
	s_waitcnt vmcnt(8)
	s_waitcnt lgkmcnt(0)
	s_barrier
	s_setprio 1
	v_mfma_f32_16x16x32_bf16 v[60:63], v[144:147], v[182:185], v[60:63]
	v_mfma_f32_16x16x32_bf16 v[56:59], v[158:161], v[182:185], v[56:59]
	v_mfma_f32_16x16x32_bf16 v[44:47], v[144:147], v[190:193], v[44:47]
	v_mfma_f32_16x16x32_bf16 v[40:43], v[158:161], v[190:193], v[40:43]
	v_mfma_f32_16x16x32_bf16 v[28:31], v[144:147], v[206:209], v[28:31]
	v_mfma_f32_16x16x32_bf16 v[24:27], v[158:161], v[206:209], v[24:27]
	v_mfma_f32_16x16x32_bf16 v[12:15], v[144:147], v[214:217], v[12:15]
	v_mfma_f32_16x16x32_bf16 v[8:11], v[158:161], v[214:217], v[8:11]
	v_mfma_f32_16x16x32_bf16 v[60:63], v[154:157], v[186:189], v[60:63]
	v_mfma_f32_16x16x32_bf16 v[56:59], v[162:165], v[186:189], v[56:59]
	v_mfma_f32_16x16x32_bf16 v[44:47], v[154:157], v[202:205], v[44:47]
	v_mfma_f32_16x16x32_bf16 v[40:43], v[162:165], v[202:205], v[40:43]
	v_mfma_f32_16x16x32_bf16 v[28:31], v[154:157], v[210:213], v[28:31]
	v_mfma_f32_16x16x32_bf16 v[24:27], v[162:165], v[210:213], v[24:27]
	v_mfma_f32_16x16x32_bf16 v[12:15], v[154:157], v[218:221], v[12:15]
	v_mfma_f32_16x16x32_bf16 v[8:11], v[162:165], v[218:221], v[8:11]
	s_setprio 0
	s_setprio 1
	v_mfma_f32_16x16x32_bf16 v[52:55], v[166:169], v[182:185], v[52:55]
	v_mfma_f32_16x16x32_bf16 v[48:51], v[174:177], v[182:185], v[48:51]
	v_mfma_f32_16x16x32_bf16 v[36:39], v[166:169], v[190:193], v[36:39]
	v_mfma_f32_16x16x32_bf16 v[32:35], v[174:177], v[190:193], v[32:35]
	v_mfma_f32_16x16x32_bf16 v[20:23], v[166:169], v[206:209], v[20:23]
	v_mfma_f32_16x16x32_bf16 v[16:19], v[174:177], v[206:209], v[16:19]
	v_mfma_f32_16x16x32_bf16 v[4:7], v[166:169], v[214:217], v[4:7]
	v_mfma_f32_16x16x32_bf16 v[0:3], v[174:177], v[214:217], v[0:3]
	v_mfma_f32_16x16x32_bf16 v[52:55], v[170:173], v[186:189], v[52:55]
	v_mfma_f32_16x16x32_bf16 v[48:51], v[178:181], v[186:189], v[48:51]
	v_mfma_f32_16x16x32_bf16 v[36:39], v[170:173], v[202:205], v[36:39]
	v_mfma_f32_16x16x32_bf16 v[32:35], v[178:181], v[202:205], v[32:35]
	v_mfma_f32_16x16x32_bf16 v[20:23], v[170:173], v[210:213], v[20:23]
	v_mfma_f32_16x16x32_bf16 v[16:19], v[178:181], v[210:213], v[16:19]
	v_mfma_f32_16x16x32_bf16 v[4:7], v[170:173], v[218:221], v[4:7]
	v_mfma_f32_16x16x32_bf16 v[0:3], v[178:181], v[218:221], v[0:3]
	s_setprio 0
	s_barrier
	s_add_i32 s51, s51, 2
	s_add_u32 s18, s18, 0x100
	s_addc_u32 s19, s19, 0
	s_add_u32 s42, s42, 0x100
	s_addc_u32 s43, s43, 0
	s_cmp_gt_u32 s51, 29
	s_cbranch_scc0 .LBB0_236
	s_and_b64 vcc, exec, s[0:1]
	s_cbranch_vccz .LBB0_239
	s_barrier

; #define PG8_STAGE(bufoff, gbase, voff) do { _Pragma("unroll") for (int _i = 0; _i < 2; ++_i) \
;         __builtin_amdgcn_global_load_lds((const unsigned*)((const char*)(gbase) + (voff)[_i]), (PG8_LAS unsigned*)(lds + (bufoff) + ldsw + _i * 8192), 16, 0, 0); } while (0)
; #define PG8_LDA(dst, b, h) do { _Pragma("unroll") for (int m = 0; m < 4; ++m) _Pragma("unroll") for (int k = 0; k < 2; ++k) dst[m][k] = *(const PG8_LAS bf16x8*)(lds + PG8_SA(b, h) + aoff + m * 2048 + k * 1024); } while (0)
; #define PG8_LDB(dst, b, h) do { _Pragma("unroll") for (int n = 0; n < 2; ++n) _Pragma("unroll") for (int k = 0; k < 2; ++k) dst[n][k] = *(const PG8_LAS bf16x8*)(lds + PG8_SB(b, h) + boff + n * 2048 + k * 1024); } while (0)
; #define PG8_MMA(ai, bj, At, Bt) do { __builtin_amdgcn_s_setprio(1); _Pragma("unroll") for (int m = 0; m < 4; ++m) _Pragma("unroll") for (int n = 0; n < 2; ++n) _Pragma("unroll") for (int k = 0; k < 2; ++k) \
;         acc[ai][bj][m][n] = __builtin_amdgcn_mfma_f32_16x16x32_bf16(Bt[n][k], At[m][k], acc[ai][bj][m][n], 0, 0, 0); __builtin_amdgcn_s_setprio(0); } while (0)
; #define PG8_WAIT_V(n) asm volatile("s_waitcnt vmcnt(" #n ")" ::: "memory")
; #define PG8_BAR __builtin_amdgcn_s_barrier()
; template <class Epi, class Sched, bool ALIGN_EPI = false, bool SP2 = false>
; __device__ __forceinline__ void gemm_phase(PG8_LAS unsigned char* lds, const Gemm g, const Sched& S, const Epi& E) {
;     ...
;         for (int t = 0; t < nt; t += 2) {
;             const bool last = (t == nt - 2);
;             const char* a1 = cA + (size_t)(t + 1) * kstep;
;             const char* a2 = last ? nA : cA + (size_t)(t + 2) * kstep; const char* b2 = last ? nB : cB + (size_t)(t + 2) * kstep;
;             const char* a3 = a2 + kstep; const char* b3 = b2 + kstep;
;             if (last && has_next) S.a_ready(nxt);
;             if constexpr (SP2) {
;             PG8_LDB(B0, 0, 0); PG8_LDB(B1, 0, 1); PG8_SCHED; PG8_LDA(At, 0, 0); PG8_STAGE(PG8_SA(1, 1), a1 + hstep, voffA);
;             PG8_WAIT_V(8); PG8_WAIT_L(0); PG8_BAR; PG8_MMA(0, 0, At, B0); PG8_MMA(0, 1, At, B1); PG8_BAR; PG8_SCHED;
;             PG8_LDA(At, 0, 1); PG8_STAGE(PG8_SB(0, 0), b2, voffB); PG8_STAGE(PG8_SB(0, 1), b2 + hstep, voffB); PG8_STAGE(PG8_SA(0, 0), a2, voffA);
;             PG8_WAIT_V(8); PG8_WAIT_L(0); PG8_BAR; PG8_MMA(1, 0, At, B0); PG8_MMA(1, 1, At, B1); PG8_BAR; PG8_SCHED;
.LBB0_892:
	s_add_u32 s12, s58, 0xfff80080
	s_addc_u32 s13, s59, -1
	s_add_i32 s84, 0, 0x10000
	s_cmp_eq_u32 s73, 28
	s_cselect_b32 s63, s18, s13
	s_cselect_b32 s62, s19, s12
	s_cselect_b32 s61, s26, s55
	s_cselect_b32 s60, s47, s49
	s_add_i32 s85, 0, 0x14000
	v_add_u32_e32 v130, s84, v247
	v_add_u32_e32 v158, s85, v247
	ds_read_b128 v[114:117], v130
	ds_read_b128 v[118:121], v130 offset:1024
	ds_read_b128 v[126:129], v130 offset:2048
	ds_read_b128 v[130:133], v130 offset:3072
	ds_read_b128 v[138:141], v158
	ds_read_b128 v[142:145], v158 offset:1024
	ds_read_b128 v[146:149], v158 offset:2048
	ds_read_b128 v[158:161], v158 offset:3072
	v_lshl_add_u64 v[214:215], s[58:59], 0, v[212:213]
	s_add_i32 m0, s57, 0xc000
	ds_read_b128 v[162:165], v249
	ds_read_b128 v[166:169], v249 offset:1024
	ds_read_b128 v[170:173], v249 offset:2048
	ds_read_b128 v[174:177], v249 offset:3072
	ds_read_b128 v[178:181], v249 offset:4096
	ds_read_b128 v[182:185], v249 offset:5120
	ds_read_b128 v[186:189], v249 offset:6144
	ds_read_b128 v[190:193], v249 offset:7168
	global_load_lds_dwordx4 v[214:215], off
	v_lshl_add_u64 v[214:215], s[58:59], 0, v[210:211]
	s_add_i32 m0, s57, 0xe000
	s_nop 0
	global_load_lds_dwordx4 v[214:215], off
	s_waitcnt vmcnt(8)
	s_waitcnt lgkmcnt(0)
	s_barrier
	s_setprio 1
	v_mfma_f32_16x16x32_bf16 v[154:157], v[114:117], v[162:165], v[154:157]
	v_mfma_f32_16x16x32_bf16 v[150:153], v[126:129], v[162:165], v[150:153]
	v_mfma_f32_16x16x32_bf16 v[110:113], v[114:117], v[170:173], v[110:113]
	v_mfma_f32_16x16x32_bf16 v[106:109], v[126:129], v[170:173], v[106:109]
	v_mfma_f32_16x16x32_bf16 v[92:95], v[114:117], v[178:181], v[92:95]
	v_mfma_f32_16x16x32_bf16 v[88:91], v[126:129], v[178:181], v[88:91]
	v_mfma_f32_16x16x32_bf16 v[76:79], v[114:117], v[186:189], v[76:79]
	v_mfma_f32_16x16x32_bf16 v[72:75], v[126:129], v[186:189], v[72:75]
	v_mfma_f32_16x16x32_bf16 v[154:157], v[118:121], v[166:169], v[154:157]
	v_mfma_f32_16x16x32_bf16 v[150:153], v[130:133], v[166:169], v[150:153]
	v_mfma_f32_16x16x32_bf16 v[110:113], v[118:121], v[174:177], v[110:113]
	v_mfma_f32_16x16x32_bf16 v[106:109], v[130:133], v[174:177], v[106:109]
	v_mfma_f32_16x16x32_bf16 v[92:95], v[118:121], v[182:185], v[92:95]
	v_mfma_f32_16x16x32_bf16 v[88:91], v[130:133], v[182:185], v[88:91]
	v_mfma_f32_16x16x32_bf16 v[76:79], v[118:121], v[190:193], v[76:79]
	v_mfma_f32_16x16x32_bf16 v[72:75], v[130:133], v[190:193], v[72:75]
	s_setprio 0
	s_setprio 1
	v_mfma_f32_16x16x32_bf16 v[134:137], v[138:141], v[162:165], v[134:137]
	v_mfma_f32_16x16x32_bf16 v[122:125], v[146:149], v[162:165], v[122:125]
	v_mfma_f32_16x16x32_bf16 v[102:105], v[138:141], v[170:173], v[102:105]
	v_mfma_f32_16x16x32_bf16 v[98:101], v[146:149], v[170:173], v[98:101]
	v_mfma_f32_16x16x32_bf16 v[84:87], v[138:141], v[178:181], v[84:87]
	v_mfma_f32_16x16x32_bf16 v[80:83], v[146:149], v[178:181], v[80:83]
	v_mfma_f32_16x16x32_bf16 v[68:71], v[138:141], v[186:189], v[68:71]
	v_mfma_f32_16x16x32_bf16 v[64:67], v[146:149], v[186:189], v[64:67]
	v_mfma_f32_16x16x32_bf16 v[134:137], v[142:145], v[166:169], v[134:137]
	v_mfma_f32_16x16x32_bf16 v[122:125], v[158:161], v[166:169], v[122:125]
	v_mfma_f32_16x16x32_bf16 v[102:105], v[142:145], v[174:177], v[102:105]
	v_mfma_f32_16x16x32_bf16 v[98:101], v[158:161], v[174:177], v[98:101]
	v_mfma_f32_16x16x32_bf16 v[84:87], v[142:145], v[182:185], v[84:87]
	v_mfma_f32_16x16x32_bf16 v[80:83], v[158:161], v[182:185], v[80:83]
	v_mfma_f32_16x16x32_bf16 v[68:71], v[142:145], v[190:193], v[68:71]
	v_mfma_f32_16x16x32_bf16 v[64:67], v[158:161], v[190:193], v[64:67]
	s_setprio 0
	s_barrier
	s_add_i32 s12, s84, s11
	v_lshl_add_u64 v[214:215], s[60:61], 0, v[204:205]
	s_mov_b32 m0, s12
	ds_read_b128 v[162:165], v249 offset:16384
	ds_read_b128 v[166:169], v249 offset:17408
	ds_read_b128 v[170:173], v249 offset:18432
	ds_read_b128 v[174:177], v249 offset:19456
	ds_read_b128 v[178:181], v249 offset:20480
	ds_read_b128 v[182:185], v249 offset:21504
	ds_read_b128 v[186:189], v249 offset:22528
	ds_read_b128 v[190:193], v249 offset:23552
	global_load_lds_dwordx4 v[214:215], off
	s_add_i32 m0, s12, 0x2000
	s_add_u32 s12, s60, 0x80000
	v_lshl_add_u64 v[216:217], s[60:61], 0, v[208:209]
	s_addc_u32 s13, s61, 0
	s_add_i32 s84, s85, s11
	global_load_lds_dwordx4 v[216:217], off
	v_lshl_add_u64 v[218:219], s[12:13], 0, v[204:205]
	s_mov_b32 m0, s84
	v_lshl_add_u64 v[220:221], s[62:63], 0, v[206:207]
	global_load_lds_dwordx4 v[218:219], off
	v_lshl_add_u64 v[218:219], s[12:13], 0, v[208:209]
	s_add_i32 m0, s84, 0x2000
	s_nop 0
	global_load_lds_dwordx4 v[218:219], off
	v_lshl_add_u64 v[218:219], s[62:63], 0, v[202:203]
	s_mov_b32 m0, s57
	s_nop 0
	global_load_lds_dwordx4 v[218:219], off
	s_mov_b32 m0, s65
	s_nop 0
	global_load_lds_dwordx4 v[220:221], off
	s_waitcnt vmcnt(8)
	s_waitcnt lgkmcnt(0)
	s_barrier
; #define PG8_STAGE(bufoff, gbase, voff) do { _Pragma("unroll") for (int _i = 0; _i < 2; ++_i) \
;         __builtin_amdgcn_global_load_lds((const unsigned*)((const char*)(gbase) + (voff)[_i]), (PG8_LAS unsigned*)(lds + (bufoff) + ldsw + _i * 8192), 16, 0, 0); } while (0)
; #define PG8_LDA(dst, b, h) do { _Pragma("unroll") for (int m = 0; m < 4; ++m) _Pragma("unroll") for (int k = 0; k < 2; ++k) dst[m][k] = *(const PG8_LAS bf16x8*)(lds + PG8_SA(b, h) + aoff + m * 2048 + k * 1024); } while (0)
; #define PG8_LDB(dst, b, h) do { _Pragma("unroll") for (int n = 0; n < 2; ++n) _Pragma("unroll") for (int k = 0; k < 2; ++k) dst[n][k] = *(const PG8_LAS bf16x8*)(lds + PG8_SB(b, h) + boff + n * 2048 + k * 1024); } while (0)
; #define PG8_MMA(ai, bj, At, Bt) do { __builtin_amdgcn_s_setprio(1); _Pragma("unroll") for (int m = 0; m < 4; ++m) _Pragma("unroll") for (int n = 0; n < 2; ++n) _Pragma("unroll") for (int k = 0; k < 2; ++k) \
;         acc[ai][bj][m][n] = __builtin_amdgcn_mfma_f32_16x16x32_bf16(Bt[n][k], At[m][k], acc[ai][bj][m][n], 0, 0, 0); __builtin_amdgcn_s_setprio(0); } while (0)
; #define PG8_WAIT_V(n) asm volatile("s_waitcnt vmcnt(" #n ")" ::: "memory")
; #define PG8_WAIT_L(n) asm volatile("s_waitcnt lgkmcnt(" #n ")" ::: "memory")
; #define PG8_BAR __builtin_amdgcn_s_barrier()
; #define PG8_SCHED __builtin_amdgcn_sched_barrier(0)
; template <class Epi, class Sched, bool ALIGN_EPI = false, bool SP2 = false>
; __device__ __forceinline__ void gemm_phase(PG8_LAS unsigned char* lds, const Gemm g, const Sched& S, const Epi& E) {
;     ...
;             PG8_WAIT_V(8); PG8_WAIT_L(0); PG8_BAR; PG8_MMA(1, 0, At, B0); PG8_MMA(1, 1, At, B1); PG8_BAR; PG8_SCHED;
;             PG8_LDB(B0, 1, 0); PG8_LDB(B1, 1, 1); PG8_SCHED; PG8_LDA(At, 1, 0); PG8_STAGE(PG8_SA(0, 1), a2 + hstep, voffA);
;             PG8_WAIT_V(8); PG8_WAIT_L(0); PG8_BAR; PG8_MMA(0, 0, At, B0); PG8_MMA(0, 1, At, B1); PG8_BAR; PG8_SCHED;
	s_setprio 1
	v_mfma_f32_16x16x32_bf16 v[60:63], v[114:117], v[162:165], v[60:63]
	v_mfma_f32_16x16x32_bf16 v[56:59], v[126:129], v[162:165], v[56:59]
	v_mfma_f32_16x16x32_bf16 v[44:47], v[114:117], v[170:173], v[44:47]
	v_mfma_f32_16x16x32_bf16 v[40:43], v[126:129], v[170:173], v[40:43]
	v_mfma_f32_16x16x32_bf16 v[28:31], v[114:117], v[178:181], v[28:31]
	v_mfma_f32_16x16x32_bf16 v[24:27], v[126:129], v[178:181], v[24:27]
	v_mfma_f32_16x16x32_bf16 v[12:15], v[114:117], v[186:189], v[12:15]
	v_mfma_f32_16x16x32_bf16 v[8:11], v[126:129], v[186:189], v[8:11]
	v_mfma_f32_16x16x32_bf16 v[60:63], v[118:121], v[166:169], v[60:63]
	v_mfma_f32_16x16x32_bf16 v[56:59], v[130:133], v[166:169], v[56:59]
	v_mfma_f32_16x16x32_bf16 v[44:47], v[118:121], v[174:177], v[44:47]
	v_mfma_f32_16x16x32_bf16 v[40:43], v[130:133], v[174:177], v[40:43]
	v_mfma_f32_16x16x32_bf16 v[28:31], v[118:121], v[182:185], v[28:31]
	v_mfma_f32_16x16x32_bf16 v[24:27], v[130:133], v[182:185], v[24:27]
	v_mfma_f32_16x16x32_bf16 v[12:15], v[118:121], v[190:193], v[12:15]
	v_mfma_f32_16x16x32_bf16 v[8:11], v[130:133], v[190:193], v[8:11]
	s_setprio 0
	s_setprio 1
	v_mfma_f32_16x16x32_bf16 v[52:55], v[138:141], v[162:165], v[52:55]
	v_mfma_f32_16x16x32_bf16 v[48:51], v[146:149], v[162:165], v[48:51]
	v_mfma_f32_16x16x32_bf16 v[36:39], v[138:141], v[170:173], v[36:39]
	v_mfma_f32_16x16x32_bf16 v[32:35], v[146:149], v[170:173], v[32:35]
	v_mfma_f32_16x16x32_bf16 v[20:23], v[138:141], v[178:181], v[20:23]
	v_mfma_f32_16x16x32_bf16 v[16:19], v[146:149], v[178:181], v[16:19]
	v_mfma_f32_16x16x32_bf16 v[4:7], v[138:141], v[186:189], v[4:7]
	v_mfma_f32_16x16x32_bf16 v[0:3], v[146:149], v[186:189], v[0:3]
	v_mfma_f32_16x16x32_bf16 v[52:55], v[142:145], v[166:169], v[52:55]
	v_mfma_f32_16x16x32_bf16 v[48:51], v[158:161], v[166:169], v[48:51]
	v_mfma_f32_16x16x32_bf16 v[36:39], v[142:145], v[174:177], v[36:39]
	v_mfma_f32_16x16x32_bf16 v[32:35], v[158:161], v[174:177], v[32:35]
	v_mfma_f32_16x16x32_bf16 v[20:23], v[142:145], v[182:185], v[20:23]
	v_mfma_f32_16x16x32_bf16 v[16:19], v[158:161], v[182:185], v[16:19]
	v_mfma_f32_16x16x32_bf16 v[4:7], v[142:145], v[190:193], v[4:7]
	v_mfma_f32_16x16x32_bf16 v[0:3], v[158:161], v[190:193], v[0:3]
	s_setprio 0
	s_barrier
	s_add_i32 s84, 0, 0x18000
	s_add_i32 s85, 0, 0x1c000
	v_add_u32_e32 v130, s84, v247
	v_add_u32_e32 v158, s85, v247
	ds_read_b128 v[114:117], v130
	ds_read_b128 v[118:121], v130 offset:1024
	ds_read_b128 v[126:129], v130 offset:2048
	ds_read_b128 v[130:133], v130 offset:3072
	ds_read_b128 v[138:141], v158
	ds_read_b128 v[142:145], v158 offset:1024
	ds_read_b128 v[146:149], v158 offset:2048
	ds_read_b128 v[158:161], v158 offset:3072
	s_add_u32 s12, s62, 0x80000
	s_addc_u32 s13, s63, 0
	s_mov_b32 m0, s66
	v_lshl_add_u64 v[222:223], s[12:13], 0, v[202:203]
	ds_read_b128 v[162:165], v249 offset:32768
	ds_read_b128 v[166:169], v249 offset:33792
	ds_read_b128 v[170:173], v249 offset:34816
	ds_read_b128 v[174:177], v249 offset:35840
	ds_read_b128 v[178:181], v249 offset:36864
	ds_read_b128 v[182:185], v249 offset:37888
	ds_read_b128 v[186:189], v249 offset:38912
	ds_read_b128 v[190:193], v249 offset:39936
	global_load_lds_dwordx4 v[222:223], off
	v_lshl_add_u64 v[222:223], s[12:13], 0, v[206:207]
	s_mov_b32 m0, s67
	s_nop 0
	global_load_lds_dwordx4 v[222:223], off
	s_waitcnt vmcnt(8)
	s_waitcnt lgkmcnt(0)
	s_barrier
	s_setprio 1
	v_mfma_f32_16x16x32_bf16 v[154:157], v[114:117], v[162:165], v[154:157]
	v_mfma_f32_16x16x32_bf16 v[150:153], v[126:129], v[162:165], v[150:153]
	v_mfma_f32_16x16x32_bf16 v[110:113], v[114:117], v[170:173], v[110:113]
	v_mfma_f32_16x16x32_bf16 v[106:109], v[126:129], v[170:173], v[106:109]
	v_mfma_f32_16x16x32_bf16 v[92:95], v[114:117], v[178:181], v[92:95]
	v_mfma_f32_16x16x32_bf16 v[88:91], v[126:129], v[178:181], v[88:91]
	v_mfma_f32_16x16x32_bf16 v[76:79], v[114:117], v[186:189], v[76:79]
	v_mfma_f32_16x16x32_bf16 v[72:75], v[126:129], v[186:189], v[72:75]
	v_mfma_f32_16x16x32_bf16 v[154:157], v[118:121], v[166:169], v[154:157]
	v_mfma_f32_16x16x32_bf16 v[150:153], v[130:133], v[166:169], v[150:153]
	v_mfma_f32_16x16x32_bf16 v[110:113], v[118:121], v[174:177], v[110:113]
	v_mfma_f32_16x16x32_bf16 v[106:109], v[130:133], v[174:177], v[106:109]
	v_mfma_f32_16x16x32_bf16 v[92:95], v[118:121], v[182:185], v[92:95]
	v_mfma_f32_16x16x32_bf16 v[88:91], v[130:133], v[182:185], v[88:91]
	v_mfma_f32_16x16x32_bf16 v[76:79], v[118:121], v[190:193], v[76:79]
	v_mfma_f32_16x16x32_bf16 v[72:75], v[130:133], v[190:193], v[72:75]
	s_setprio 0
	s_setprio 1
	v_mfma_f32_16x16x32_bf16 v[134:137], v[138:141], v[162:165], v[134:137]
	v_mfma_f32_16x16x32_bf16 v[122:125], v[146:149], v[162:165], v[122:125]
	v_mfma_f32_16x16x32_bf16 v[102:105], v[138:141], v[170:173], v[102:105]
	v_mfma_f32_16x16x32_bf16 v[98:101], v[146:149], v[170:173], v[98:101]
	v_mfma_f32_16x16x32_bf16 v[84:87], v[138:141], v[178:181], v[84:87]
	v_mfma_f32_16x16x32_bf16 v[80:83], v[146:149], v[178:181], v[80:83]
	v_mfma_f32_16x16x32_bf16 v[68:71], v[138:141], v[186:189], v[68:71]
	v_mfma_f32_16x16x32_bf16 v[64:67], v[146:149], v[186:189], v[64:67]
	v_mfma_f32_16x16x32_bf16 v[134:137], v[142:145], v[166:169], v[134:137]
	v_mfma_f32_16x16x32_bf16 v[122:125], v[158:161], v[166:169], v[122:125]
	v_mfma_f32_16x16x32_bf16 v[102:105], v[142:145], v[174:177], v[102:105]
	v_mfma_f32_16x16x32_bf16 v[98:101], v[158:161], v[174:177], v[98:101]
	v_mfma_f32_16x16x32_bf16 v[84:87], v[142:145], v[182:185], v[84:87]
	v_mfma_f32_16x16x32_bf16 v[80:83], v[158:161], v[182:185], v[80:83]
	v_mfma_f32_16x16x32_bf16 v[68:71], v[142:145], v[190:193], v[68:71]
	v_mfma_f32_16x16x32_bf16 v[64:67], v[158:161], v[190:193], v[64:67]
	s_setprio 0
	s_barrier
; #define PG8_STAGE(bufoff, gbase, voff) do { _Pragma("unroll") for (int _i = 0; _i < 2; ++_i) \
;         __builtin_amdgcn_global_load_lds((const unsigned*)((const char*)(gbase) + (voff)[_i]), (PG8_LAS unsigned*)(lds + (bufoff) + ldsw + _i * 8192), 16, 0, 0); } while (0)
; #define PG8_LDA(dst, b, h) do { _Pragma("unroll") for (int m = 0; m < 4; ++m) _Pragma("unroll") for (int k = 0; k < 2; ++k) dst[m][k] = *(const PG8_LAS bf16x8*)(lds + PG8_SA(b, h) + aoff + m * 2048 + k * 1024); } while (0)
; #define PG8_MMA(ai, bj, At, Bt) do { __builtin_amdgcn_s_setprio(1); _Pragma("unroll") for (int m = 0; m < 4; ++m) _Pragma("unroll") for (int n = 0; n < 2; ++n) _Pragma("unroll") for (int k = 0; k < 2; ++k) \
;         acc[ai][bj][m][n] = __builtin_amdgcn_mfma_f32_16x16x32_bf16(Bt[n][k], At[m][k], acc[ai][bj][m][n], 0, 0, 0); __builtin_amdgcn_s_setprio(0); } while (0)
; #define PG8_WAIT_V(n) asm volatile("s_waitcnt vmcnt(" #n ")" ::: "memory")
; #define PG8_WAIT_L(n) asm volatile("s_waitcnt lgkmcnt(" #n ")" ::: "memory")
; #define PG8_BAR __builtin_amdgcn_s_barrier()
; #define PG8_SCHED __builtin_amdgcn_sched_barrier(0)
; template <class Epi, class Sched, bool ALIGN_EPI = false, bool SP2 = false>
; __device__ __forceinline__ void gemm_phase(PG8_LAS unsigned char* lds, const Gemm g, const Sched& S, const Epi& E) {
;     ...
;         for (int t = 0; t < nt; t += 2) {
;             const bool last = (t == nt - 2);
;     ...
;             PG8_LDA(At, 1, 1); PG8_STAGE(PG8_SB(1, 0), b3, voffB); PG8_STAGE(PG8_SB(1, 1), b3 + hstep, voffB); PG8_STAGE(PG8_SA(1, 0), a3, voffA);
;             PG8_WAIT_V(8); PG8_WAIT_L(0); PG8_BAR; PG8_MMA(1, 0, At, B0); PG8_MMA(1, 1, At, B1); PG8_BAR; PG8_SCHED;
	s_add_i32 s12, s84, s11
	v_lshl_add_u64 v[214:215], v[214:215], 0, s[36:37]
	s_mov_b32 m0, s12
	ds_read_b128 v[162:165], v249 offset:49152
	ds_read_b128 v[166:169], v249 offset:50176
	ds_read_b128 v[170:173], v249 offset:51200
	ds_read_b128 v[174:177], v249 offset:52224
	ds_read_b128 v[178:181], v249 offset:53248
	ds_read_b128 v[182:185], v249 offset:54272
	ds_read_b128 v[186:189], v249 offset:55296
	ds_read_b128 v[190:193], v249 offset:56320
	global_load_lds_dwordx4 v[214:215], off
	s_add_i32 m0, s12, 0x2000
	s_add_u32 s12, s60, 0x80080
	v_lshl_add_u64 v[214:215], v[216:217], 0, s[36:37]
	s_addc_u32 s13, s61, 0
	s_add_i32 s60, s85, s11
	global_load_lds_dwordx4 v[214:215], off
	v_lshl_add_u64 v[214:215], s[12:13], 0, v[204:205]
	s_mov_b32 m0, s60
	s_nop 0
	global_load_lds_dwordx4 v[214:215], off
	v_lshl_add_u64 v[214:215], s[12:13], 0, v[208:209]
	s_add_i32 m0, s60, 0x2000
	s_nop 0
	global_load_lds_dwordx4 v[214:215], off
	v_lshl_add_u64 v[214:215], v[218:219], 0, s[36:37]
	s_mov_b32 m0, s69
	s_nop 0
	global_load_lds_dwordx4 v[214:215], off
	v_lshl_add_u64 v[214:215], v[220:221], 0, s[36:37]
	s_mov_b32 m0, s70
	s_nop 0
	global_load_lds_dwordx4 v[214:215], off
	s_waitcnt vmcnt(8)
	s_waitcnt lgkmcnt(0)
	s_barrier
	s_setprio 1
	v_mfma_f32_16x16x32_bf16 v[60:63], v[114:117], v[162:165], v[60:63]
	v_mfma_f32_16x16x32_bf16 v[56:59], v[126:129], v[162:165], v[56:59]
	v_mfma_f32_16x16x32_bf16 v[44:47], v[114:117], v[170:173], v[44:47]
	v_mfma_f32_16x16x32_bf16 v[40:43], v[126:129], v[170:173], v[40:43]
	v_mfma_f32_16x16x32_bf16 v[28:31], v[114:117], v[178:181], v[28:31]
	v_mfma_f32_16x16x32_bf16 v[24:27], v[126:129], v[178:181], v[24:27]
	v_mfma_f32_16x16x32_bf16 v[12:15], v[114:117], v[186:189], v[12:15]
	v_mfma_f32_16x16x32_bf16 v[8:11], v[126:129], v[186:189], v[8:11]
	v_mfma_f32_16x16x32_bf16 v[60:63], v[118:121], v[166:169], v[60:63]
	v_mfma_f32_16x16x32_bf16 v[56:59], v[130:133], v[166:169], v[56:59]
	v_mfma_f32_16x16x32_bf16 v[44:47], v[118:121], v[174:177], v[44:47]
	v_mfma_f32_16x16x32_bf16 v[40:43], v[130:133], v[174:177], v[40:43]
	v_mfma_f32_16x16x32_bf16 v[28:31], v[118:121], v[182:185], v[28:31]
	v_mfma_f32_16x16x32_bf16 v[24:27], v[130:133], v[182:185], v[24:27]
	v_mfma_f32_16x16x32_bf16 v[12:15], v[118:121], v[190:193], v[12:15]
	v_mfma_f32_16x16x32_bf16 v[8:11], v[130:133], v[190:193], v[8:11]
	s_setprio 0
	s_setprio 1
	v_mfma_f32_16x16x32_bf16 v[52:55], v[138:141], v[162:165], v[52:55]
	v_mfma_f32_16x16x32_bf16 v[48:51], v[146:149], v[162:165], v[48:51]
	v_mfma_f32_16x16x32_bf16 v[36:39], v[138:141], v[170:173], v[36:39]
	v_mfma_f32_16x16x32_bf16 v[32:35], v[146:149], v[170:173], v[32:35]
	v_mfma_f32_16x16x32_bf16 v[20:23], v[138:141], v[178:181], v[20:23]
	v_mfma_f32_16x16x32_bf16 v[16:19], v[146:149], v[178:181], v[16:19]
	v_mfma_f32_16x16x32_bf16 v[4:7], v[138:141], v[186:189], v[4:7]
	v_mfma_f32_16x16x32_bf16 v[0:3], v[146:149], v[186:189], v[0:3]
	v_mfma_f32_16x16x32_bf16 v[52:55], v[142:145], v[166:169], v[52:55]
	v_mfma_f32_16x16x32_bf16 v[48:51], v[158:161], v[166:169], v[48:51]
	v_mfma_f32_16x16x32_bf16 v[36:39], v[142:145], v[174:177], v[36:39]
	v_mfma_f32_16x16x32_bf16 v[32:35], v[158:161], v[174:177], v[32:35]
	v_mfma_f32_16x16x32_bf16 v[20:23], v[142:145], v[182:185], v[20:23]
	v_mfma_f32_16x16x32_bf16 v[16:19], v[158:161], v[182:185], v[16:19]
	v_mfma_f32_16x16x32_bf16 v[4:7], v[142:145], v[190:193], v[4:7]
	v_mfma_f32_16x16x32_bf16 v[0:3], v[158:161], v[190:193], v[0:3]
	s_setprio 0
	s_barrier
	s_add_i32 s73, s73, 2
	s_add_u32 s49, s49, 0x100
	s_addc_u32 s55, s55, 0
	s_add_u32 s58, s58, 0x100
	s_addc_u32 s59, s59, 0
	s_cmp_gt_u32 s73, 29
	s_cbranch_scc0 .LBB0_892
	s_and_b64 vcc, exec, s[14:15]
	s_cbranch_vccz .LBB0_895
	s_barrier

; #define PG8_STAGE(bufoff, gbase, voff) do { _Pragma("unroll") for (int _i = 0; _i < 2; ++_i) \
;         __builtin_amdgcn_global_load_lds((const unsigned*)((const char*)(gbase) + (voff)[_i]), (PG8_LAS unsigned*)(lds + (bufoff) + ldsw + _i * 8192), 16, 0, 0); } while (0)
; #define PG8_LDA(dst, b, h) do { _Pragma("unroll") for (int m = 0; m < 4; ++m) _Pragma("unroll") for (int k = 0; k < 2; ++k) dst[m][k] = *(const PG8_LAS bf16x8*)(lds + PG8_SA(b, h) + aoff + m * 2048 + k * 1024); } while (0)
; #define PG8_LDB(dst, b, h) do { _Pragma("unroll") for (int n = 0; n < 2; ++n) _Pragma("unroll") for (int k = 0; k < 2; ++k) dst[n][k] = *(const PG8_LAS bf16x8*)(lds + PG8_SB(b, h) + boff + n * 2048 + k * 1024); } while (0)
; #define PG8_MMA(ai, bj, At, Bt) do { __builtin_amdgcn_s_setprio(1); _Pragma("unroll") for (int m = 0; m < 4; ++m) _Pragma("unroll") for (int n = 0; n < 2; ++n) _Pragma("unroll") for (int k = 0; k < 2; ++k) \
;         acc[ai][bj][m][n] = __builtin_amdgcn_mfma_f32_16x16x32_bf16(Bt[n][k], At[m][k], acc[ai][bj][m][n], 0, 0, 0); __builtin_amdgcn_s_setprio(0); } while (0)
; #define PG8_WAIT_V(n) asm volatile("s_waitcnt vmcnt(" #n ")" ::: "memory")
; #define PG8_BAR __builtin_amdgcn_s_barrier()
; template <class Epi, class Sched, bool ALIGN_EPI = false, bool SP2 = false>
; __device__ __forceinline__ void gemm_phase(PG8_LAS unsigned char* lds, const Gemm g, const Sched& S, const Epi& E) {
;     ...
;         for (int t = 0; t < nt; t += 2) {
;             const bool last = (t == nt - 2);
;             const char* a1 = cA + (size_t)(t + 1) * kstep;
;             const char* a2 = last ? nA : cA + (size_t)(t + 2) * kstep; const char* b2 = last ? nB : cB + (size_t)(t + 2) * kstep;
;             const char* a3 = a2 + kstep; const char* b3 = b2 + kstep;
;             if (last && has_next) S.a_ready(nxt);
;             if constexpr (SP2) {
;             PG8_LDB(B0, 0, 0); PG8_LDB(B1, 0, 1); PG8_SCHED; PG8_LDA(At, 0, 0); PG8_STAGE(PG8_SA(1, 1), a1 + hstep, voffA);
;             PG8_WAIT_V(8); PG8_WAIT_L(0); PG8_BAR; PG8_MMA(0, 0, At, B0); PG8_MMA(0, 1, At, B1); PG8_BAR; PG8_SCHED;
;             PG8_LDA(At, 0, 1); PG8_STAGE(PG8_SB(0, 0), b2, voffB); PG8_STAGE(PG8_SB(0, 1), b2 + hstep, voffB); PG8_STAGE(PG8_SA(0, 0), a2, voffA);
;             PG8_WAIT_V(8); PG8_WAIT_L(0); PG8_BAR; PG8_MMA(1, 0, At, B0); PG8_MMA(1, 1, At, B1); PG8_BAR; PG8_SCHED;
.LBB0_1016:
	s_add_u32 s12, s14, 0xfff80080
	s_addc_u32 s13, s15, -1
	s_add_i32 s70, 0, 0x10000
	s_cmp_eq_u32 s69, 28
	s_cselect_b32 s59, s1, s13
	s_cselect_b32 s58, s5, s12
	v_add_u32_e32 v148, s70, v149
	s_cselect_b32 s43, s10, s53
	s_cselect_b32 s42, s11, s51
	s_add_i32 s71, 0, 0x14000
	ds_read_b128 v[144:147], v148
	ds_read_b128 v[154:157], v148 offset:1024
	ds_read_b128 v[158:161], v148 offset:2048
	ds_read_b128 v[162:165], v148 offset:3072
	v_add_u32_e32 v148, s71, v149
	ds_read_b128 v[166:169], v148
	ds_read_b128 v[170:173], v148 offset:1024
	ds_read_b128 v[174:177], v148 offset:2048
	ds_read_b128 v[178:181], v148 offset:3072
	v_lshl_add_u64 v[222:223], s[14:15], 0, v[142:143]
	s_add_i32 m0, s61, 0xc000
	ds_read_b128 v[182:185], v152
	ds_read_b128 v[186:189], v152 offset:1024
	ds_read_b128 v[190:193], v152 offset:2048
	ds_read_b128 v[202:205], v152 offset:3072
	ds_read_b128 v[206:209], v152 offset:4096
	ds_read_b128 v[210:213], v152 offset:5120
	ds_read_b128 v[214:217], v152 offset:6144
	ds_read_b128 v[218:221], v152 offset:7168
	global_load_lds_dwordx4 v[222:223], off
	v_lshl_add_u64 v[222:223], s[14:15], 0, v[140:141]
	s_add_i32 m0, s61, 0xe000
	s_nop 0
	global_load_lds_dwordx4 v[222:223], off
	s_waitcnt vmcnt(8)
	s_waitcnt lgkmcnt(0)
	s_barrier
	s_setprio 1
	v_mfma_f32_16x16x32_bf16 v[126:129], v[144:147], v[182:185], v[126:129]
	v_mfma_f32_16x16x32_bf16 v[122:125], v[158:161], v[182:185], v[122:125]
	v_mfma_f32_16x16x32_bf16 v[110:113], v[144:147], v[190:193], v[110:113]
	v_mfma_f32_16x16x32_bf16 v[106:109], v[158:161], v[190:193], v[106:109]
	v_mfma_f32_16x16x32_bf16 v[92:95], v[144:147], v[206:209], v[92:95]
	v_mfma_f32_16x16x32_bf16 v[88:91], v[158:161], v[206:209], v[88:91]
	v_mfma_f32_16x16x32_bf16 v[76:79], v[144:147], v[214:217], v[76:79]
	v_mfma_f32_16x16x32_bf16 v[72:75], v[158:161], v[214:217], v[72:75]
	v_mfma_f32_16x16x32_bf16 v[126:129], v[154:157], v[186:189], v[126:129]
	v_mfma_f32_16x16x32_bf16 v[122:125], v[162:165], v[186:189], v[122:125]
	v_mfma_f32_16x16x32_bf16 v[110:113], v[154:157], v[202:205], v[110:113]
	v_mfma_f32_16x16x32_bf16 v[106:109], v[162:165], v[202:205], v[106:109]
	v_mfma_f32_16x16x32_bf16 v[92:95], v[154:157], v[210:213], v[92:95]
	v_mfma_f32_16x16x32_bf16 v[88:91], v[162:165], v[210:213], v[88:91]
	v_mfma_f32_16x16x32_bf16 v[76:79], v[154:157], v[218:221], v[76:79]
	v_mfma_f32_16x16x32_bf16 v[72:75], v[162:165], v[218:221], v[72:75]
	s_setprio 0
	s_setprio 1
	v_mfma_f32_16x16x32_bf16 v[118:121], v[166:169], v[182:185], v[118:121]
	v_mfma_f32_16x16x32_bf16 v[114:117], v[174:177], v[182:185], v[114:117]
	v_mfma_f32_16x16x32_bf16 v[102:105], v[166:169], v[190:193], v[102:105]
	v_mfma_f32_16x16x32_bf16 v[98:101], v[174:177], v[190:193], v[98:101]
	v_mfma_f32_16x16x32_bf16 v[84:87], v[166:169], v[206:209], v[84:87]
	v_mfma_f32_16x16x32_bf16 v[80:83], v[174:177], v[206:209], v[80:83]
	v_mfma_f32_16x16x32_bf16 v[68:71], v[166:169], v[214:217], v[68:71]
	v_mfma_f32_16x16x32_bf16 v[64:67], v[174:177], v[214:217], v[64:67]
	v_mfma_f32_16x16x32_bf16 v[118:121], v[170:173], v[186:189], v[118:121]
	v_mfma_f32_16x16x32_bf16 v[114:117], v[178:181], v[186:189], v[114:117]
	v_mfma_f32_16x16x32_bf16 v[102:105], v[170:173], v[202:205], v[102:105]
	v_mfma_f32_16x16x32_bf16 v[98:101], v[178:181], v[202:205], v[98:101]
	v_mfma_f32_16x16x32_bf16 v[84:87], v[170:173], v[210:213], v[84:87]
	v_mfma_f32_16x16x32_bf16 v[80:83], v[178:181], v[210:213], v[80:83]
	v_mfma_f32_16x16x32_bf16 v[68:71], v[170:173], v[218:221], v[68:71]
	v_mfma_f32_16x16x32_bf16 v[64:67], v[178:181], v[218:221], v[64:67]
	s_setprio 0
	s_barrier
	s_add_i32 s12, s70, s9
	v_lshl_add_u64 v[222:223], s[42:43], 0, v[132:133]
	s_mov_b32 m0, s12
	ds_read_b128 v[182:185], v152 offset:16384
	ds_read_b128 v[186:189], v152 offset:17408
	ds_read_b128 v[190:193], v152 offset:18432
	ds_read_b128 v[202:205], v152 offset:19456
	ds_read_b128 v[206:209], v152 offset:20480
	ds_read_b128 v[210:213], v152 offset:21504
	ds_read_b128 v[214:217], v152 offset:22528
	ds_read_b128 v[218:221], v152 offset:23552
	global_load_lds_dwordx4 v[222:223], off
	s_add_i32 m0, s12, 0x2000
	s_add_u32 s12, s42, 0x80000
	v_lshl_add_u64 v[224:225], s[42:43], 0, v[136:137]
	s_addc_u32 s13, s43, 0
	s_add_i32 s70, s71, s9
	global_load_lds_dwordx4 v[224:225], off
	v_lshl_add_u64 v[226:227], s[12:13], 0, v[132:133]
	s_mov_b32 m0, s70
	v_lshl_add_u64 v[228:229], s[58:59], 0, v[134:135]
	global_load_lds_dwordx4 v[226:227], off
	v_lshl_add_u64 v[226:227], s[12:13], 0, v[136:137]
	s_add_i32 m0, s70, 0x2000
	s_nop 0
	global_load_lds_dwordx4 v[226:227], off
	v_lshl_add_u64 v[226:227], s[58:59], 0, v[130:131]
	s_mov_b32 m0, s61
	s_nop 0
	global_load_lds_dwordx4 v[226:227], off
	s_mov_b32 m0, s62
	s_nop 0
	global_load_lds_dwordx4 v[228:229], off
	s_waitcnt vmcnt(8)
	s_waitcnt lgkmcnt(0)
	s_barrier
; #define PG8_STAGE(bufoff, gbase, voff) do { _Pragma("unroll") for (int _i = 0; _i < 2; ++_i) \
;         __builtin_amdgcn_global_load_lds((const unsigned*)((const char*)(gbase) + (voff)[_i]), (PG8_LAS unsigned*)(lds + (bufoff) + ldsw + _i * 8192), 16, 0, 0); } while (0)
; #define PG8_LDA(dst, b, h) do { _Pragma("unroll") for (int m = 0; m < 4; ++m) _Pragma("unroll") for (int k = 0; k < 2; ++k) dst[m][k] = *(const PG8_LAS bf16x8*)(lds + PG8_SA(b, h) + aoff + m * 2048 + k * 1024); } while (0)
; #define PG8_LDB(dst, b, h) do { _Pragma("unroll") for (int n = 0; n < 2; ++n) _Pragma("unroll") for (int k = 0; k < 2; ++k) dst[n][k] = *(const PG8_LAS bf16x8*)(lds + PG8_SB(b, h) + boff + n * 2048 + k * 1024); } while (0)
; #define PG8_MMA(ai, bj, At, Bt) do { __builtin_amdgcn_s_setprio(1); _Pragma("unroll") for (int m = 0; m < 4; ++m) _Pragma("unroll") for (int n = 0; n < 2; ++n) _Pragma("unroll") for (int k = 0; k < 2; ++k) \
;         acc[ai][bj][m][n] = __builtin_amdgcn_mfma_f32_16x16x32_bf16(Bt[n][k], At[m][k], acc[ai][bj][m][n], 0, 0, 0); __builtin_amdgcn_s_setprio(0); } while (0)
; #define PG8_WAIT_V(n) asm volatile("s_waitcnt vmcnt(" #n ")" ::: "memory")
; #define PG8_WAIT_L(n) asm volatile("s_waitcnt lgkmcnt(" #n ")" ::: "memory")
; #define PG8_BAR __builtin_amdgcn_s_barrier()
; #define PG8_SCHED __builtin_amdgcn_sched_barrier(0)
; template <class Epi, class Sched, bool ALIGN_EPI = false, bool SP2 = false>
; __device__ __forceinline__ void gemm_phase(PG8_LAS unsigned char* lds, const Gemm g, const Sched& S, const Epi& E) {
;     ...
;             PG8_WAIT_V(8); PG8_WAIT_L(0); PG8_BAR; PG8_MMA(1, 0, At, B0); PG8_MMA(1, 1, At, B1); PG8_BAR; PG8_SCHED;
;             PG8_LDB(B0, 1, 0); PG8_LDB(B1, 1, 1); PG8_SCHED; PG8_LDA(At, 1, 0); PG8_STAGE(PG8_SA(0, 1), a2 + hstep, voffA);
;             PG8_WAIT_V(8); PG8_WAIT_L(0); PG8_BAR; PG8_MMA(0, 0, At, B0); PG8_MMA(0, 1, At, B1); PG8_BAR; PG8_SCHED;
	s_setprio 1
	v_mfma_f32_16x16x32_bf16 v[60:63], v[144:147], v[182:185], v[60:63]
	v_mfma_f32_16x16x32_bf16 v[56:59], v[158:161], v[182:185], v[56:59]
	v_mfma_f32_16x16x32_bf16 v[44:47], v[144:147], v[190:193], v[44:47]
	v_mfma_f32_16x16x32_bf16 v[40:43], v[158:161], v[190:193], v[40:43]
	v_mfma_f32_16x16x32_bf16 v[28:31], v[144:147], v[206:209], v[28:31]
	v_mfma_f32_16x16x32_bf16 v[24:27], v[158:161], v[206:209], v[24:27]
	v_mfma_f32_16x16x32_bf16 v[12:15], v[144:147], v[214:217], v[12:15]
	v_mfma_f32_16x16x32_bf16 v[8:11], v[158:161], v[214:217], v[8:11]
	v_mfma_f32_16x16x32_bf16 v[60:63], v[154:157], v[186:189], v[60:63]
	v_mfma_f32_16x16x32_bf16 v[56:59], v[162:165], v[186:189], v[56:59]
	v_mfma_f32_16x16x32_bf16 v[44:47], v[154:157], v[202:205], v[44:47]
	v_mfma_f32_16x16x32_bf16 v[40:43], v[162:165], v[202:205], v[40:43]
	v_mfma_f32_16x16x32_bf16 v[28:31], v[154:157], v[210:213], v[28:31]
	v_mfma_f32_16x16x32_bf16 v[24:27], v[162:165], v[210:213], v[24:27]
	v_mfma_f32_16x16x32_bf16 v[12:15], v[154:157], v[218:221], v[12:15]
	v_mfma_f32_16x16x32_bf16 v[8:11], v[162:165], v[218:221], v[8:11]
	s_setprio 0
	s_setprio 1
	v_mfma_f32_16x16x32_bf16 v[52:55], v[166:169], v[182:185], v[52:55]
	v_mfma_f32_16x16x32_bf16 v[48:51], v[174:177], v[182:185], v[48:51]
	v_mfma_f32_16x16x32_bf16 v[36:39], v[166:169], v[190:193], v[36:39]
	v_mfma_f32_16x16x32_bf16 v[32:35], v[174:177], v[190:193], v[32:35]
	v_mfma_f32_16x16x32_bf16 v[20:23], v[166:169], v[206:209], v[20:23]
	v_mfma_f32_16x16x32_bf16 v[16:19], v[174:177], v[206:209], v[16:19]
	v_mfma_f32_16x16x32_bf16 v[4:7], v[166:169], v[214:217], v[4:7]
	v_mfma_f32_16x16x32_bf16 v[0:3], v[174:177], v[214:217], v[0:3]
	v_mfma_f32_16x16x32_bf16 v[52:55], v[170:173], v[186:189], v[52:55]
	v_mfma_f32_16x16x32_bf16 v[48:51], v[178:181], v[186:189], v[48:51]
	v_mfma_f32_16x16x32_bf16 v[36:39], v[170:173], v[202:205], v[36:39]
	v_mfma_f32_16x16x32_bf16 v[32:35], v[178:181], v[202:205], v[32:35]
	v_mfma_f32_16x16x32_bf16 v[20:23], v[170:173], v[210:213], v[20:23]
	v_mfma_f32_16x16x32_bf16 v[16:19], v[178:181], v[210:213], v[16:19]
	v_mfma_f32_16x16x32_bf16 v[4:7], v[170:173], v[218:221], v[4:7]
	v_mfma_f32_16x16x32_bf16 v[0:3], v[178:181], v[218:221], v[0:3]
	s_setprio 0
	s_barrier
	s_add_i32 s70, 0, 0x18000
	v_add_u32_e32 v148, s70, v149
	s_add_i32 s71, 0, 0x1c000
	ds_read_b128 v[144:147], v148
	ds_read_b128 v[154:157], v148 offset:1024
	ds_read_b128 v[158:161], v148 offset:2048
	ds_read_b128 v[162:165], v148 offset:3072
	v_add_u32_e32 v148, s71, v149
	ds_read_b128 v[166:169], v148
	ds_read_b128 v[170:173], v148 offset:1024
	ds_read_b128 v[174:177], v148 offset:2048
	ds_read_b128 v[178:181], v148 offset:3072
	s_add_u32 s12, s58, 0x80000
	s_addc_u32 s13, s59, 0
	s_mov_b32 m0, s63
	v_lshl_add_u64 v[230:231], s[12:13], 0, v[130:131]
	ds_read_b128 v[182:185], v152 offset:32768
	ds_read_b128 v[186:189], v152 offset:33792
	ds_read_b128 v[190:193], v152 offset:34816
	ds_read_b128 v[202:205], v152 offset:35840
	ds_read_b128 v[206:209], v152 offset:36864
	ds_read_b128 v[210:213], v152 offset:37888
	ds_read_b128 v[214:217], v152 offset:38912
	ds_read_b128 v[218:221], v152 offset:39936
	global_load_lds_dwordx4 v[230:231], off
	v_lshl_add_u64 v[230:231], s[12:13], 0, v[134:135]
	s_mov_b32 m0, s65
	s_nop 0
	global_load_lds_dwordx4 v[230:231], off
	s_waitcnt vmcnt(8)
	s_waitcnt lgkmcnt(0)
	s_barrier
	s_setprio 1
	v_mfma_f32_16x16x32_bf16 v[126:129], v[144:147], v[182:185], v[126:129]
	v_mfma_f32_16x16x32_bf16 v[122:125], v[158:161], v[182:185], v[122:125]
	v_mfma_f32_16x16x32_bf16 v[110:113], v[144:147], v[190:193], v[110:113]
	v_mfma_f32_16x16x32_bf16 v[106:109], v[158:161], v[190:193], v[106:109]
	v_mfma_f32_16x16x32_bf16 v[92:95], v[144:147], v[206:209], v[92:95]
	v_mfma_f32_16x16x32_bf16 v[88:91], v[158:161], v[206:209], v[88:91]
	v_mfma_f32_16x16x32_bf16 v[76:79], v[144:147], v[214:217], v[76:79]
	v_mfma_f32_16x16x32_bf16 v[72:75], v[158:161], v[214:217], v[72:75]
	v_mfma_f32_16x16x32_bf16 v[126:129], v[154:157], v[186:189], v[126:129]
	v_mfma_f32_16x16x32_bf16 v[122:125], v[162:165], v[186:189], v[122:125]
	v_mfma_f32_16x16x32_bf16 v[110:113], v[154:157], v[202:205], v[110:113]
	v_mfma_f32_16x16x32_bf16 v[106:109], v[162:165], v[202:205], v[106:109]
	v_mfma_f32_16x16x32_bf16 v[92:95], v[154:157], v[210:213], v[92:95]
	v_mfma_f32_16x16x32_bf16 v[88:91], v[162:165], v[210:213], v[88:91]
	v_mfma_f32_16x16x32_bf16 v[76:79], v[154:157], v[218:221], v[76:79]
	v_mfma_f32_16x16x32_bf16 v[72:75], v[162:165], v[218:221], v[72:75]
	s_setprio 0
	s_setprio 1
	v_mfma_f32_16x16x32_bf16 v[118:121], v[166:169], v[182:185], v[118:121]
	v_mfma_f32_16x16x32_bf16 v[114:117], v[174:177], v[182:185], v[114:117]
	v_mfma_f32_16x16x32_bf16 v[102:105], v[166:169], v[190:193], v[102:105]
	v_mfma_f32_16x16x32_bf16 v[98:101], v[174:177], v[190:193], v[98:101]
	v_mfma_f32_16x16x32_bf16 v[84:87], v[166:169], v[206:209], v[84:87]
	v_mfma_f32_16x16x32_bf16 v[80:83], v[174:177], v[206:209], v[80:83]
	v_mfma_f32_16x16x32_bf16 v[68:71], v[166:169], v[214:217], v[68:71]
	v_mfma_f32_16x16x32_bf16 v[64:67], v[174:177], v[214:217], v[64:67]
	v_mfma_f32_16x16x32_bf16 v[118:121], v[170:173], v[186:189], v[118:121]
	v_mfma_f32_16x16x32_bf16 v[114:117], v[178:181], v[186:189], v[114:117]
	v_mfma_f32_16x16x32_bf16 v[102:105], v[170:173], v[202:205], v[102:105]
	v_mfma_f32_16x16x32_bf16 v[98:101], v[178:181], v[202:205], v[98:101]
	v_mfma_f32_16x16x32_bf16 v[84:87], v[170:173], v[210:213], v[84:87]
	v_mfma_f32_16x16x32_bf16 v[80:83], v[178:181], v[210:213], v[80:83]
	v_mfma_f32_16x16x32_bf16 v[68:71], v[170:173], v[218:221], v[68:71]
	v_mfma_f32_16x16x32_bf16 v[64:67], v[178:181], v[218:221], v[64:67]
	s_setprio 0
	s_barrier
; #define PG8_STAGE(bufoff, gbase, voff) do { _Pragma("unroll") for (int _i = 0; _i < 2; ++_i) \
;         __builtin_amdgcn_global_load_lds((const unsigned*)((const char*)(gbase) + (voff)[_i]), (PG8_LAS unsigned*)(lds + (bufoff) + ldsw + _i * 8192), 16, 0, 0); } while (0)
; #define PG8_LDA(dst, b, h) do { _Pragma("unroll") for (int m = 0; m < 4; ++m) _Pragma("unroll") for (int k = 0; k < 2; ++k) dst[m][k] = *(const PG8_LAS bf16x8*)(lds + PG8_SA(b, h) + aoff + m * 2048 + k * 1024); } while (0)
; #define PG8_MMA(ai, bj, At, Bt) do { __builtin_amdgcn_s_setprio(1); _Pragma("unroll") for (int m = 0; m < 4; ++m) _Pragma("unroll") for (int n = 0; n < 2; ++n) _Pragma("unroll") for (int k = 0; k < 2; ++k) \
;         acc[ai][bj][m][n] = __builtin_amdgcn_mfma_f32_16x16x32_bf16(Bt[n][k], At[m][k], acc[ai][bj][m][n], 0, 0, 0); __builtin_amdgcn_s_setprio(0); } while (0)
; #define PG8_WAIT_V(n) asm volatile("s_waitcnt vmcnt(" #n ")" ::: "memory")
; #define PG8_WAIT_L(n) asm volatile("s_waitcnt lgkmcnt(" #n ")" ::: "memory")
; #define PG8_BAR __builtin_amdgcn_s_barrier()
; #define PG8_SCHED __builtin_amdgcn_sched_barrier(0)
; template <class Epi, class Sched, bool ALIGN_EPI = false, bool SP2 = false>
; __device__ __forceinline__ void gemm_phase(PG8_LAS unsigned char* lds, const Gemm g, const Sched& S, const Epi& E) {
;     ...
;         for (int t = 0; t < nt; t += 2) {
;             const bool last = (t == nt - 2);
;     ...
;             PG8_LDA(At, 1, 1); PG8_STAGE(PG8_SB(1, 0), b3, voffB); PG8_STAGE(PG8_SB(1, 1), b3 + hstep, voffB); PG8_STAGE(PG8_SA(1, 0), a3, voffA);
;             PG8_WAIT_V(8); PG8_WAIT_L(0); PG8_BAR; PG8_MMA(1, 0, At, B0); PG8_MMA(1, 1, At, B1); PG8_BAR; PG8_SCHED;
	s_add_i32 s12, s70, s9
	v_lshl_add_u64 v[222:223], v[222:223], 0, s[36:37]
	s_mov_b32 m0, s12
	ds_read_b128 v[182:185], v152 offset:49152
	ds_read_b128 v[186:189], v152 offset:50176
	ds_read_b128 v[190:193], v152 offset:51200
	ds_read_b128 v[202:205], v152 offset:52224
	ds_read_b128 v[206:209], v152 offset:53248
	ds_read_b128 v[210:213], v152 offset:54272
	ds_read_b128 v[214:217], v152 offset:55296
	ds_read_b128 v[218:221], v152 offset:56320
	global_load_lds_dwordx4 v[222:223], off
	s_add_i32 m0, s12, 0x2000
	s_add_u32 s12, s42, 0x80080
	v_lshl_add_u64 v[222:223], v[224:225], 0, s[36:37]
	s_addc_u32 s13, s43, 0
	s_add_i32 s42, s71, s9
	global_load_lds_dwordx4 v[222:223], off
	v_lshl_add_u64 v[222:223], s[12:13], 0, v[132:133]
	s_mov_b32 m0, s42
	s_nop 0
	global_load_lds_dwordx4 v[222:223], off
	v_lshl_add_u64 v[222:223], s[12:13], 0, v[136:137]
	s_add_i32 m0, s42, 0x2000
	s_nop 0
	global_load_lds_dwordx4 v[222:223], off
	v_lshl_add_u64 v[222:223], v[226:227], 0, s[36:37]
	s_mov_b32 m0, s66
	s_nop 0
	global_load_lds_dwordx4 v[222:223], off
	v_lshl_add_u64 v[222:223], v[228:229], 0, s[36:37]
	s_mov_b32 m0, s67
	s_nop 0
	global_load_lds_dwordx4 v[222:223], off
	s_waitcnt vmcnt(8)
	s_waitcnt lgkmcnt(0)
	s_barrier
	s_setprio 1
	v_mfma_f32_16x16x32_bf16 v[60:63], v[144:147], v[182:185], v[60:63]
	v_mfma_f32_16x16x32_bf16 v[56:59], v[158:161], v[182:185], v[56:59]
	v_mfma_f32_16x16x32_bf16 v[44:47], v[144:147], v[190:193], v[44:47]
	v_mfma_f32_16x16x32_bf16 v[40:43], v[158:161], v[190:193], v[40:43]
	v_mfma_f32_16x16x32_bf16 v[28:31], v[144:147], v[206:209], v[28:31]
	v_mfma_f32_16x16x32_bf16 v[24:27], v[158:161], v[206:209], v[24:27]
	v_mfma_f32_16x16x32_bf16 v[12:15], v[144:147], v[214:217], v[12:15]
	v_mfma_f32_16x16x32_bf16 v[8:11], v[158:161], v[214:217], v[8:11]
	v_mfma_f32_16x16x32_bf16 v[60:63], v[154:157], v[186:189], v[60:63]
	v_mfma_f32_16x16x32_bf16 v[56:59], v[162:165], v[186:189], v[56:59]
	v_mfma_f32_16x16x32_bf16 v[44:47], v[154:157], v[202:205], v[44:47]
	v_mfma_f32_16x16x32_bf16 v[40:43], v[162:165], v[202:205], v[40:43]
	v_mfma_f32_16x16x32_bf16 v[28:31], v[154:157], v[210:213], v[28:31]
	v_mfma_f32_16x16x32_bf16 v[24:27], v[162:165], v[210:213], v[24:27]
	v_mfma_f32_16x16x32_bf16 v[12:15], v[154:157], v[218:221], v[12:15]
	v_mfma_f32_16x16x32_bf16 v[8:11], v[162:165], v[218:221], v[8:11]
	s_setprio 0
	s_setprio 1
	v_mfma_f32_16x16x32_bf16 v[52:55], v[166:169], v[182:185], v[52:55]
	v_mfma_f32_16x16x32_bf16 v[48:51], v[174:177], v[182:185], v[48:51]
	v_mfma_f32_16x16x32_bf16 v[36:39], v[166:169], v[190:193], v[36:39]
	v_mfma_f32_16x16x32_bf16 v[32:35], v[174:177], v[190:193], v[32:35]
	v_mfma_f32_16x16x32_bf16 v[20:23], v[166:169], v[206:209], v[20:23]
	v_mfma_f32_16x16x32_bf16 v[16:19], v[174:177], v[206:209], v[16:19]
	v_mfma_f32_16x16x32_bf16 v[4:7], v[166:169], v[214:217], v[4:7]
	v_mfma_f32_16x16x32_bf16 v[0:3], v[174:177], v[214:217], v[0:3]
	v_mfma_f32_16x16x32_bf16 v[52:55], v[170:173], v[186:189], v[52:55]
	v_mfma_f32_16x16x32_bf16 v[48:51], v[178:181], v[186:189], v[48:51]
	v_mfma_f32_16x16x32_bf16 v[36:39], v[170:173], v[202:205], v[36:39]
	v_mfma_f32_16x16x32_bf16 v[32:35], v[178:181], v[202:205], v[32:35]
	v_mfma_f32_16x16x32_bf16 v[20:23], v[170:173], v[210:213], v[20:23]
	v_mfma_f32_16x16x32_bf16 v[16:19], v[178:181], v[210:213], v[16:19]
	v_mfma_f32_16x16x32_bf16 v[4:7], v[170:173], v[218:221], v[4:7]
	v_mfma_f32_16x16x32_bf16 v[0:3], v[178:181], v[218:221], v[0:3]
	s_setprio 0
	s_barrier
	s_add_i32 s69, s69, 2
	s_add_u32 s51, s51, 0x100
	s_addc_u32 s53, s53, 0
	s_add_u32 s14, s14, 0x100
	s_addc_u32 s15, s15, 0
	s_cmp_gt_u32 s69, 29
	s_cbranch_scc0 .LBB0_1016
	s_and_b64 vcc, exec, s[48:49]
	s_cbranch_vccz .LBB0_1019
	s_barrier

; #define PG8_STAGE(bufoff, gbase, voff) do { _Pragma("unroll") for (int _i = 0; _i < 2; ++_i) \
;         __builtin_amdgcn_global_load_lds((const unsigned*)((const char*)(gbase) + (voff)[_i]), (PG8_LAS unsigned*)(lds + (bufoff) + ldsw + _i * 8192), 16, 0, 0); } while (0)
; #define PG8_LDA(dst, b, h) do { _Pragma("unroll") for (int m = 0; m < 4; ++m) _Pragma("unroll") for (int k = 0; k < 2; ++k) dst[m][k] = *(const PG8_LAS bf16x8*)(lds + PG8_SA(b, h) + aoff + m * 2048 + k * 1024); } while (0)
; #define PG8_LDB(dst, b, h) do { _Pragma("unroll") for (int n = 0; n < 2; ++n) _Pragma("unroll") for (int k = 0; k < 2; ++k) dst[n][k] = *(const PG8_LAS bf16x8*)(lds + PG8_SB(b, h) + boff + n * 2048 + k * 1024); } while (0)
; #define PG8_MMA(ai, bj, At, Bt) do { __builtin_amdgcn_s_setprio(1); _Pragma("unroll") for (int m = 0; m < 4; ++m) _Pragma("unroll") for (int n = 0; n < 2; ++n) _Pragma("unroll") for (int k = 0; k < 2; ++k) \
;         acc[ai][bj][m][n] = __builtin_amdgcn_mfma_f32_16x16x32_bf16(Bt[n][k], At[m][k], acc[ai][bj][m][n], 0, 0, 0); __builtin_amdgcn_s_setprio(0); } while (0)
; #define PG8_WAIT_V(n) asm volatile("s_waitcnt vmcnt(" #n ")" ::: "memory")
; #define PG8_BAR __builtin_amdgcn_s_barrier()
; template <class Epi, class Sched, bool ALIGN_EPI = false, bool SP2 = false>
; __device__ __forceinline__ void gemm_phase(PG8_LAS unsigned char* lds, const Gemm g, const Sched& S, const Epi& E) {
;     ...
;         for (int t = 0; t < nt; t += 2) {
;             const bool last = (t == nt - 2);
;             const char* a1 = cA + (size_t)(t + 1) * kstep;
;             const char* a2 = last ? nA : cA + (size_t)(t + 2) * kstep; const char* b2 = last ? nB : cB + (size_t)(t + 2) * kstep;
;             const char* a3 = a2 + kstep; const char* b3 = b2 + kstep;
;             if (last && has_next) S.a_ready(nxt);
;             if constexpr (SP2) {
;             PG8_LDB(B0, 0, 0); PG8_LDB(B1, 0, 1); PG8_SCHED; PG8_LDA(At, 0, 0); PG8_STAGE(PG8_SA(1, 1), a1 + hstep, voffA);
;             PG8_WAIT_V(8); PG8_WAIT_L(0); PG8_BAR; PG8_MMA(0, 0, At, B0); PG8_MMA(0, 1, At, B1); PG8_BAR; PG8_SCHED;
;             PG8_LDA(At, 0, 1); PG8_STAGE(PG8_SB(0, 0), b2, voffB); PG8_STAGE(PG8_SB(0, 1), b2 + hstep, voffB); PG8_STAGE(PG8_SA(0, 0), a2, voffA);
;             PG8_WAIT_V(8); PG8_WAIT_L(0); PG8_BAR; PG8_MMA(1, 0, At, B0); PG8_MMA(1, 1, At, B1); PG8_BAR; PG8_SCHED;
.LBB0_1144:
	s_add_u32 s12, s58, 0xffe00080
	s_addc_u32 s13, s59, -1
	s_add_i32 s84, 0, 0x10000
	s_cmpk_eq_i32 s73, 0x7c
	s_cselect_b32 s63, s18, s13
	s_cselect_b32 s62, s19, s12
	s_cselect_b32 s61, s26, s55
	s_cselect_b32 s60, s47, s49
	s_add_i32 s85, 0, 0x14000
	v_add_u32_e32 v130, s84, v247
	v_add_u32_e32 v158, s85, v247
	ds_read_b128 v[114:117], v130
	ds_read_b128 v[118:121], v130 offset:1024
	ds_read_b128 v[126:129], v130 offset:2048
	ds_read_b128 v[130:133], v130 offset:3072
	ds_read_b128 v[138:141], v158
	ds_read_b128 v[142:145], v158 offset:1024
	ds_read_b128 v[146:149], v158 offset:2048
	ds_read_b128 v[158:161], v158 offset:3072
	v_lshl_add_u64 v[214:215], s[58:59], 0, v[212:213]
	s_add_i32 m0, s57, 0xc000
	ds_read_b128 v[162:165], v249
	ds_read_b128 v[166:169], v249 offset:1024
	ds_read_b128 v[170:173], v249 offset:2048
	ds_read_b128 v[174:177], v249 offset:3072
	ds_read_b128 v[178:181], v249 offset:4096
	ds_read_b128 v[182:185], v249 offset:5120
	ds_read_b128 v[186:189], v249 offset:6144
	ds_read_b128 v[190:193], v249 offset:7168
	global_load_lds_dwordx4 v[214:215], off
	v_lshl_add_u64 v[214:215], s[58:59], 0, v[210:211]
	s_add_i32 m0, s57, 0xe000
	s_nop 0
	global_load_lds_dwordx4 v[214:215], off
	s_waitcnt vmcnt(8)
	s_waitcnt lgkmcnt(0)
	s_barrier
	s_setprio 1
	v_mfma_f32_16x16x32_bf16 v[154:157], v[114:117], v[162:165], v[154:157]
	v_mfma_f32_16x16x32_bf16 v[150:153], v[126:129], v[162:165], v[150:153]
	v_mfma_f32_16x16x32_bf16 v[110:113], v[114:117], v[170:173], v[110:113]
	v_mfma_f32_16x16x32_bf16 v[106:109], v[126:129], v[170:173], v[106:109]
	v_mfma_f32_16x16x32_bf16 v[92:95], v[114:117], v[178:181], v[92:95]
	v_mfma_f32_16x16x32_bf16 v[88:91], v[126:129], v[178:181], v[88:91]
	v_mfma_f32_16x16x32_bf16 v[76:79], v[114:117], v[186:189], v[76:79]
	v_mfma_f32_16x16x32_bf16 v[72:75], v[126:129], v[186:189], v[72:75]
	v_mfma_f32_16x16x32_bf16 v[154:157], v[118:121], v[166:169], v[154:157]
	v_mfma_f32_16x16x32_bf16 v[150:153], v[130:133], v[166:169], v[150:153]
	v_mfma_f32_16x16x32_bf16 v[110:113], v[118:121], v[174:177], v[110:113]
	v_mfma_f32_16x16x32_bf16 v[106:109], v[130:133], v[174:177], v[106:109]
	v_mfma_f32_16x16x32_bf16 v[92:95], v[118:121], v[182:185], v[92:95]
	v_mfma_f32_16x16x32_bf16 v[88:91], v[130:133], v[182:185], v[88:91]
	v_mfma_f32_16x16x32_bf16 v[76:79], v[118:121], v[190:193], v[76:79]
	v_mfma_f32_16x16x32_bf16 v[72:75], v[130:133], v[190:193], v[72:75]
	s_setprio 0
	s_setprio 1
	v_mfma_f32_16x16x32_bf16 v[134:137], v[138:141], v[162:165], v[134:137]
	v_mfma_f32_16x16x32_bf16 v[122:125], v[146:149], v[162:165], v[122:125]
	v_mfma_f32_16x16x32_bf16 v[102:105], v[138:141], v[170:173], v[102:105]
	v_mfma_f32_16x16x32_bf16 v[98:101], v[146:149], v[170:173], v[98:101]
	v_mfma_f32_16x16x32_bf16 v[84:87], v[138:141], v[178:181], v[84:87]
	v_mfma_f32_16x16x32_bf16 v[80:83], v[146:149], v[178:181], v[80:83]
	v_mfma_f32_16x16x32_bf16 v[68:71], v[138:141], v[186:189], v[68:71]
	v_mfma_f32_16x16x32_bf16 v[64:67], v[146:149], v[186:189], v[64:67]
	v_mfma_f32_16x16x32_bf16 v[134:137], v[142:145], v[166:169], v[134:137]
	v_mfma_f32_16x16x32_bf16 v[122:125], v[158:161], v[166:169], v[122:125]
	v_mfma_f32_16x16x32_bf16 v[102:105], v[142:145], v[174:177], v[102:105]
	v_mfma_f32_16x16x32_bf16 v[98:101], v[158:161], v[174:177], v[98:101]
	v_mfma_f32_16x16x32_bf16 v[84:87], v[142:145], v[182:185], v[84:87]
	v_mfma_f32_16x16x32_bf16 v[80:83], v[158:161], v[182:185], v[80:83]
	v_mfma_f32_16x16x32_bf16 v[68:71], v[142:145], v[190:193], v[68:71]
	v_mfma_f32_16x16x32_bf16 v[64:67], v[158:161], v[190:193], v[64:67]
	s_setprio 0
	s_barrier
	s_add_i32 s12, s84, s11
	v_lshl_add_u64 v[214:215], s[60:61], 0, v[204:205]
	s_mov_b32 m0, s12
	ds_read_b128 v[162:165], v249 offset:16384
	ds_read_b128 v[166:169], v249 offset:17408
	ds_read_b128 v[170:173], v249 offset:18432
	ds_read_b128 v[174:177], v249 offset:19456
	ds_read_b128 v[178:181], v249 offset:20480
	ds_read_b128 v[182:185], v249 offset:21504
	ds_read_b128 v[186:189], v249 offset:22528
	ds_read_b128 v[190:193], v249 offset:23552
	global_load_lds_dwordx4 v[214:215], off
	s_add_i32 m0, s12, 0x2000
	s_add_u32 s12, s60, 0x200000
	v_lshl_add_u64 v[216:217], s[60:61], 0, v[208:209]
	s_addc_u32 s13, s61, 0
	s_add_i32 s84, s85, s11
	global_load_lds_dwordx4 v[216:217], off
	v_lshl_add_u64 v[218:219], s[12:13], 0, v[204:205]
	s_mov_b32 m0, s84
	v_lshl_add_u64 v[220:221], s[62:63], 0, v[206:207]
	global_load_lds_dwordx4 v[218:219], off
	v_lshl_add_u64 v[218:219], s[12:13], 0, v[208:209]
	s_add_i32 m0, s84, 0x2000
	s_nop 0
	global_load_lds_dwordx4 v[218:219], off
	v_lshl_add_u64 v[218:219], s[62:63], 0, v[202:203]
	s_mov_b32 m0, s57
	s_nop 0
	global_load_lds_dwordx4 v[218:219], off
	s_mov_b32 m0, s65
	s_nop 0
	global_load_lds_dwordx4 v[220:221], off
	s_waitcnt vmcnt(8)
	s_waitcnt lgkmcnt(0)
	s_barrier
; #define PG8_STAGE(bufoff, gbase, voff) do { _Pragma("unroll") for (int _i = 0; _i < 2; ++_i) \
;         __builtin_amdgcn_global_load_lds((const unsigned*)((const char*)(gbase) + (voff)[_i]), (PG8_LAS unsigned*)(lds + (bufoff) + ldsw + _i * 8192), 16, 0, 0); } while (0)
; #define PG8_LDA(dst, b, h) do { _Pragma("unroll") for (int m = 0; m < 4; ++m) _Pragma("unroll") for (int k = 0; k < 2; ++k) dst[m][k] = *(const PG8_LAS bf16x8*)(lds + PG8_SA(b, h) + aoff + m * 2048 + k * 1024); } while (0)
; #define PG8_LDB(dst, b, h) do { _Pragma("unroll") for (int n = 0; n < 2; ++n) _Pragma("unroll") for (int k = 0; k < 2; ++k) dst[n][k] = *(const PG8_LAS bf16x8*)(lds + PG8_SB(b, h) + boff + n * 2048 + k * 1024); } while (0)
; #define PG8_MMA(ai, bj, At, Bt) do { __builtin_amdgcn_s_setprio(1); _Pragma("unroll") for (int m = 0; m < 4; ++m) _Pragma("unroll") for (int n = 0; n < 2; ++n) _Pragma("unroll") for (int k = 0; k < 2; ++k) \
;         acc[ai][bj][m][n] = __builtin_amdgcn_mfma_f32_16x16x32_bf16(Bt[n][k], At[m][k], acc[ai][bj][m][n], 0, 0, 0); __builtin_amdgcn_s_setprio(0); } while (0)
; #define PG8_WAIT_V(n) asm volatile("s_waitcnt vmcnt(" #n ")" ::: "memory")
; #define PG8_WAIT_L(n) asm volatile("s_waitcnt lgkmcnt(" #n ")" ::: "memory")
; #define PG8_BAR __builtin_amdgcn_s_barrier()
; #define PG8_SCHED __builtin_amdgcn_sched_barrier(0)
; template <class Epi, class Sched, bool ALIGN_EPI = false, bool SP2 = false>
; __device__ __forceinline__ void gemm_phase(PG8_LAS unsigned char* lds, const Gemm g, const Sched& S, const Epi& E) {
;     ...
;             PG8_WAIT_V(8); PG8_WAIT_L(0); PG8_BAR; PG8_MMA(1, 0, At, B0); PG8_MMA(1, 1, At, B1); PG8_BAR; PG8_SCHED;
;             PG8_LDB(B0, 1, 0); PG8_LDB(B1, 1, 1); PG8_SCHED; PG8_LDA(At, 1, 0); PG8_STAGE(PG8_SA(0, 1), a2 + hstep, voffA);
;             PG8_WAIT_V(8); PG8_WAIT_L(0); PG8_BAR; PG8_MMA(0, 0, At, B0); PG8_MMA(0, 1, At, B1); PG8_BAR; PG8_SCHED;
	s_setprio 1
	v_mfma_f32_16x16x32_bf16 v[60:63], v[114:117], v[162:165], v[60:63]
	v_mfma_f32_16x16x32_bf16 v[56:59], v[126:129], v[162:165], v[56:59]
	v_mfma_f32_16x16x32_bf16 v[44:47], v[114:117], v[170:173], v[44:47]
	v_mfma_f32_16x16x32_bf16 v[40:43], v[126:129], v[170:173], v[40:43]
	v_mfma_f32_16x16x32_bf16 v[28:31], v[114:117], v[178:181], v[28:31]
	v_mfma_f32_16x16x32_bf16 v[24:27], v[126:129], v[178:181], v[24:27]
	v_mfma_f32_16x16x32_bf16 v[12:15], v[114:117], v[186:189], v[12:15]
	v_mfma_f32_16x16x32_bf16 v[8:11], v[126:129], v[186:189], v[8:11]
	v_mfma_f32_16x16x32_bf16 v[60:63], v[118:121], v[166:169], v[60:63]
	v_mfma_f32_16x16x32_bf16 v[56:59], v[130:133], v[166:169], v[56:59]
	v_mfma_f32_16x16x32_bf16 v[44:47], v[118:121], v[174:177], v[44:47]
	v_mfma_f32_16x16x32_bf16 v[40:43], v[130:133], v[174:177], v[40:43]
	v_mfma_f32_16x16x32_bf16 v[28:31], v[118:121], v[182:185], v[28:31]
	v_mfma_f32_16x16x32_bf16 v[24:27], v[130:133], v[182:185], v[24:27]
	v_mfma_f32_16x16x32_bf16 v[12:15], v[118:121], v[190:193], v[12:15]
	v_mfma_f32_16x16x32_bf16 v[8:11], v[130:133], v[190:193], v[8:11]
	s_setprio 0
	s_setprio 1
	v_mfma_f32_16x16x32_bf16 v[52:55], v[138:141], v[162:165], v[52:55]
	v_mfma_f32_16x16x32_bf16 v[48:51], v[146:149], v[162:165], v[48:51]
	v_mfma_f32_16x16x32_bf16 v[36:39], v[138:141], v[170:173], v[36:39]
	v_mfma_f32_16x16x32_bf16 v[32:35], v[146:149], v[170:173], v[32:35]
	v_mfma_f32_16x16x32_bf16 v[20:23], v[138:141], v[178:181], v[20:23]
	v_mfma_f32_16x16x32_bf16 v[16:19], v[146:149], v[178:181], v[16:19]
	v_mfma_f32_16x16x32_bf16 v[4:7], v[138:141], v[186:189], v[4:7]
	v_mfma_f32_16x16x32_bf16 v[0:3], v[146:149], v[186:189], v[0:3]
	v_mfma_f32_16x16x32_bf16 v[52:55], v[142:145], v[166:169], v[52:55]
	v_mfma_f32_16x16x32_bf16 v[48:51], v[158:161], v[166:169], v[48:51]
	v_mfma_f32_16x16x32_bf16 v[36:39], v[142:145], v[174:177], v[36:39]
	v_mfma_f32_16x16x32_bf16 v[32:35], v[158:161], v[174:177], v[32:35]
	v_mfma_f32_16x16x32_bf16 v[20:23], v[142:145], v[182:185], v[20:23]
	v_mfma_f32_16x16x32_bf16 v[16:19], v[158:161], v[182:185], v[16:19]
	v_mfma_f32_16x16x32_bf16 v[4:7], v[142:145], v[190:193], v[4:7]
	v_mfma_f32_16x16x32_bf16 v[0:3], v[158:161], v[190:193], v[0:3]
	s_setprio 0
	s_barrier
	s_add_i32 s84, 0, 0x18000
	s_add_i32 s85, 0, 0x1c000
	v_add_u32_e32 v130, s84, v247
	v_add_u32_e32 v158, s85, v247
	ds_read_b128 v[114:117], v130
	ds_read_b128 v[118:121], v130 offset:1024
	ds_read_b128 v[126:129], v130 offset:2048
	ds_read_b128 v[130:133], v130 offset:3072
	ds_read_b128 v[138:141], v158
	ds_read_b128 v[142:145], v158 offset:1024
	ds_read_b128 v[146:149], v158 offset:2048
	ds_read_b128 v[158:161], v158 offset:3072
	s_add_u32 s12, s62, 0x200000
	s_addc_u32 s13, s63, 0
	s_mov_b32 m0, s66
	v_lshl_add_u64 v[222:223], s[12:13], 0, v[202:203]
	ds_read_b128 v[162:165], v249 offset:32768
	ds_read_b128 v[166:169], v249 offset:33792
	ds_read_b128 v[170:173], v249 offset:34816
	ds_read_b128 v[174:177], v249 offset:35840
	ds_read_b128 v[178:181], v249 offset:36864
	ds_read_b128 v[182:185], v249 offset:37888
	ds_read_b128 v[186:189], v249 offset:38912
	ds_read_b128 v[190:193], v249 offset:39936
	global_load_lds_dwordx4 v[222:223], off
	v_lshl_add_u64 v[222:223], s[12:13], 0, v[206:207]
	s_mov_b32 m0, s67
	s_nop 0
	global_load_lds_dwordx4 v[222:223], off
	s_waitcnt vmcnt(8)
	s_waitcnt lgkmcnt(0)
	s_barrier
	s_setprio 1
	v_mfma_f32_16x16x32_bf16 v[154:157], v[114:117], v[162:165], v[154:157]
	v_mfma_f32_16x16x32_bf16 v[150:153], v[126:129], v[162:165], v[150:153]
	v_mfma_f32_16x16x32_bf16 v[110:113], v[114:117], v[170:173], v[110:113]
	v_mfma_f32_16x16x32_bf16 v[106:109], v[126:129], v[170:173], v[106:109]
	v_mfma_f32_16x16x32_bf16 v[92:95], v[114:117], v[178:181], v[92:95]
	v_mfma_f32_16x16x32_bf16 v[88:91], v[126:129], v[178:181], v[88:91]
	v_mfma_f32_16x16x32_bf16 v[76:79], v[114:117], v[186:189], v[76:79]
	v_mfma_f32_16x16x32_bf16 v[72:75], v[126:129], v[186:189], v[72:75]
	v_mfma_f32_16x16x32_bf16 v[154:157], v[118:121], v[166:169], v[154:157]
	v_mfma_f32_16x16x32_bf16 v[150:153], v[130:133], v[166:169], v[150:153]
	v_mfma_f32_16x16x32_bf16 v[110:113], v[118:121], v[174:177], v[110:113]
	v_mfma_f32_16x16x32_bf16 v[106:109], v[130:133], v[174:177], v[106:109]
	v_mfma_f32_16x16x32_bf16 v[92:95], v[118:121], v[182:185], v[92:95]
	v_mfma_f32_16x16x32_bf16 v[88:91], v[130:133], v[182:185], v[88:91]
	v_mfma_f32_16x16x32_bf16 v[76:79], v[118:121], v[190:193], v[76:79]
	v_mfma_f32_16x16x32_bf16 v[72:75], v[130:133], v[190:193], v[72:75]
	s_setprio 0
	s_setprio 1
	v_mfma_f32_16x16x32_bf16 v[134:137], v[138:141], v[162:165], v[134:137]
	v_mfma_f32_16x16x32_bf16 v[122:125], v[146:149], v[162:165], v[122:125]
	v_mfma_f32_16x16x32_bf16 v[102:105], v[138:141], v[170:173], v[102:105]
	v_mfma_f32_16x16x32_bf16 v[98:101], v[146:149], v[170:173], v[98:101]
	v_mfma_f32_16x16x32_bf16 v[84:87], v[138:141], v[178:181], v[84:87]
	v_mfma_f32_16x16x32_bf16 v[80:83], v[146:149], v[178:181], v[80:83]
	v_mfma_f32_16x16x32_bf16 v[68:71], v[138:141], v[186:189], v[68:71]
	v_mfma_f32_16x16x32_bf16 v[64:67], v[146:149], v[186:189], v[64:67]
	v_mfma_f32_16x16x32_bf16 v[134:137], v[142:145], v[166:169], v[134:137]
	v_mfma_f32_16x16x32_bf16 v[122:125], v[158:161], v[166:169], v[122:125]
	v_mfma_f32_16x16x32_bf16 v[102:105], v[142:145], v[174:177], v[102:105]
	v_mfma_f32_16x16x32_bf16 v[98:101], v[158:161], v[174:177], v[98:101]
	v_mfma_f32_16x16x32_bf16 v[84:87], v[142:145], v[182:185], v[84:87]
	v_mfma_f32_16x16x32_bf16 v[80:83], v[158:161], v[182:185], v[80:83]
	v_mfma_f32_16x16x32_bf16 v[68:71], v[142:145], v[190:193], v[68:71]
	v_mfma_f32_16x16x32_bf16 v[64:67], v[158:161], v[190:193], v[64:67]
	s_setprio 0
	s_barrier
; #define PG8_STAGE(bufoff, gbase, voff) do { _Pragma("unroll") for (int _i = 0; _i < 2; ++_i) \
;         __builtin_amdgcn_global_load_lds((const unsigned*)((const char*)(gbase) + (voff)[_i]), (PG8_LAS unsigned*)(lds + (bufoff) + ldsw + _i * 8192), 16, 0, 0); } while (0)
; #define PG8_LDA(dst, b, h) do { _Pragma("unroll") for (int m = 0; m < 4; ++m) _Pragma("unroll") for (int k = 0; k < 2; ++k) dst[m][k] = *(const PG8_LAS bf16x8*)(lds + PG8_SA(b, h) + aoff + m * 2048 + k * 1024); } while (0)
; #define PG8_MMA(ai, bj, At, Bt) do { __builtin_amdgcn_s_setprio(1); _Pragma("unroll") for (int m = 0; m < 4; ++m) _Pragma("unroll") for (int n = 0; n < 2; ++n) _Pragma("unroll") for (int k = 0; k < 2; ++k) \
;         acc[ai][bj][m][n] = __builtin_amdgcn_mfma_f32_16x16x32_bf16(Bt[n][k], At[m][k], acc[ai][bj][m][n], 0, 0, 0); __builtin_amdgcn_s_setprio(0); } while (0)
; #define PG8_WAIT_V(n) asm volatile("s_waitcnt vmcnt(" #n ")" ::: "memory")
; #define PG8_WAIT_L(n) asm volatile("s_waitcnt lgkmcnt(" #n ")" ::: "memory")
; #define PG8_BAR __builtin_amdgcn_s_barrier()
; #define PG8_SCHED __builtin_amdgcn_sched_barrier(0)
; template <class Epi, class Sched, bool ALIGN_EPI = false, bool SP2 = false>
; __device__ __forceinline__ void gemm_phase(PG8_LAS unsigned char* lds, const Gemm g, const Sched& S, const Epi& E) {
;     ...
;         for (int t = 0; t < nt; t += 2) {
;             const bool last = (t == nt - 2);
;     ...
;             PG8_LDA(At, 1, 1); PG8_STAGE(PG8_SB(1, 0), b3, voffB); PG8_STAGE(PG8_SB(1, 1), b3 + hstep, voffB); PG8_STAGE(PG8_SA(1, 0), a3, voffA);
;             PG8_WAIT_V(8); PG8_WAIT_L(0); PG8_BAR; PG8_MMA(1, 0, At, B0); PG8_MMA(1, 1, At, B1); PG8_BAR; PG8_SCHED;
	s_add_i32 s12, s84, s11
	v_lshl_add_u64 v[214:215], v[214:215], 0, s[36:37]
	s_mov_b32 m0, s12
	ds_read_b128 v[162:165], v249 offset:49152
	ds_read_b128 v[166:169], v249 offset:50176
	ds_read_b128 v[170:173], v249 offset:51200
	ds_read_b128 v[174:177], v249 offset:52224
	ds_read_b128 v[178:181], v249 offset:53248
	ds_read_b128 v[182:185], v249 offset:54272
	ds_read_b128 v[186:189], v249 offset:55296
	ds_read_b128 v[190:193], v249 offset:56320
	global_load_lds_dwordx4 v[214:215], off
	s_add_i32 m0, s12, 0x2000
	s_add_u32 s12, s60, 0x200080
	v_lshl_add_u64 v[214:215], v[216:217], 0, s[36:37]
	s_addc_u32 s13, s61, 0
	s_add_i32 s60, s85, s11
	global_load_lds_dwordx4 v[214:215], off
	v_lshl_add_u64 v[214:215], s[12:13], 0, v[204:205]
	s_mov_b32 m0, s60
	s_nop 0
	global_load_lds_dwordx4 v[214:215], off
	v_lshl_add_u64 v[214:215], s[12:13], 0, v[208:209]
	s_add_i32 m0, s60, 0x2000
	s_nop 0
	global_load_lds_dwordx4 v[214:215], off
	v_lshl_add_u64 v[214:215], v[218:219], 0, s[36:37]
	s_mov_b32 m0, s69
	s_nop 0
	global_load_lds_dwordx4 v[214:215], off
	v_lshl_add_u64 v[214:215], v[220:221], 0, s[36:37]
	s_mov_b32 m0, s70
	s_nop 0
	global_load_lds_dwordx4 v[214:215], off
	s_waitcnt vmcnt(8)
	s_waitcnt lgkmcnt(0)
	s_barrier
	s_setprio 1
	v_mfma_f32_16x16x32_bf16 v[60:63], v[114:117], v[162:165], v[60:63]
	v_mfma_f32_16x16x32_bf16 v[56:59], v[126:129], v[162:165], v[56:59]
	v_mfma_f32_16x16x32_bf16 v[44:47], v[114:117], v[170:173], v[44:47]
	v_mfma_f32_16x16x32_bf16 v[40:43], v[126:129], v[170:173], v[40:43]
	v_mfma_f32_16x16x32_bf16 v[28:31], v[114:117], v[178:181], v[28:31]
	v_mfma_f32_16x16x32_bf16 v[24:27], v[126:129], v[178:181], v[24:27]
	v_mfma_f32_16x16x32_bf16 v[12:15], v[114:117], v[186:189], v[12:15]
	v_mfma_f32_16x16x32_bf16 v[8:11], v[126:129], v[186:189], v[8:11]
	v_mfma_f32_16x16x32_bf16 v[60:63], v[118:121], v[166:169], v[60:63]
	v_mfma_f32_16x16x32_bf16 v[56:59], v[130:133], v[166:169], v[56:59]
	v_mfma_f32_16x16x32_bf16 v[44:47], v[118:121], v[174:177], v[44:47]
	v_mfma_f32_16x16x32_bf16 v[40:43], v[130:133], v[174:177], v[40:43]
	v_mfma_f32_16x16x32_bf16 v[28:31], v[118:121], v[182:185], v[28:31]
	v_mfma_f32_16x16x32_bf16 v[24:27], v[130:133], v[182:185], v[24:27]
	v_mfma_f32_16x16x32_bf16 v[12:15], v[118:121], v[190:193], v[12:15]
	v_mfma_f32_16x16x32_bf16 v[8:11], v[130:133], v[190:193], v[8:11]
	s_setprio 0
	s_setprio 1
	v_mfma_f32_16x16x32_bf16 v[52:55], v[138:141], v[162:165], v[52:55]
	v_mfma_f32_16x16x32_bf16 v[48:51], v[146:149], v[162:165], v[48:51]
	v_mfma_f32_16x16x32_bf16 v[36:39], v[138:141], v[170:173], v[36:39]
	v_mfma_f32_16x16x32_bf16 v[32:35], v[146:149], v[170:173], v[32:35]
	v_mfma_f32_16x16x32_bf16 v[20:23], v[138:141], v[178:181], v[20:23]
	v_mfma_f32_16x16x32_bf16 v[16:19], v[146:149], v[178:181], v[16:19]
	v_mfma_f32_16x16x32_bf16 v[4:7], v[138:141], v[186:189], v[4:7]
	v_mfma_f32_16x16x32_bf16 v[0:3], v[146:149], v[186:189], v[0:3]
	v_mfma_f32_16x16x32_bf16 v[52:55], v[142:145], v[166:169], v[52:55]
	v_mfma_f32_16x16x32_bf16 v[48:51], v[158:161], v[166:169], v[48:51]
	v_mfma_f32_16x16x32_bf16 v[36:39], v[142:145], v[174:177], v[36:39]
	v_mfma_f32_16x16x32_bf16 v[32:35], v[158:161], v[174:177], v[32:35]
	v_mfma_f32_16x16x32_bf16 v[20:23], v[142:145], v[182:185], v[20:23]
	v_mfma_f32_16x16x32_bf16 v[16:19], v[158:161], v[182:185], v[16:19]
	v_mfma_f32_16x16x32_bf16 v[4:7], v[142:145], v[190:193], v[4:7]
	v_mfma_f32_16x16x32_bf16 v[0:3], v[158:161], v[190:193], v[0:3]
	s_setprio 0
	s_barrier
	s_add_i32 s73, s73, 2
	s_add_u32 s49, s49, 0x100
	s_addc_u32 s55, s55, 0
	s_add_u32 s58, s58, 0x100
	s_addc_u32 s59, s59, 0
	s_cmpk_gt_u32 s73, 0x7d
	s_cbranch_scc0 .LBB0_1144
	s_and_b64 vcc, exec, s[14:15]
	s_cbranch_vccz .LBB0_1147
	s_barrier
